# v26 + loop-edge edit: K-loop counter/pointer SALU moved from after the closing barrier into the last MFMA cluster (4 GEMM loops)
# baseline (speedup 1.0000x reference)
; #define PG8_STAGE(bufoff, gbase, voff) do { _Pragma("unroll") for (int _i = 0; _i < 2; ++_i) \
;         __builtin_amdgcn_global_load_lds((const unsigned*)((const char*)(gbase) + (voff)[_i]), (LAS unsigned*)(lds + (bufoff) + ldsw + _i * 8192), 16, 0, 0); } while (0)
; #define PG8_LDA(dst, b, h) do { _Pragma("unroll") for (int m = 0; m < 4; ++m) _Pragma("unroll") for (int k = 0; k < 2; ++k) dst[m][k] = *(const LAS bf16x8*)(lds + PG8_SA(b, h) + aoff + m * 2048 + k * 1024); } while (0)
; #define PG8_LDB(dst, b, h) do { _Pragma("unroll") for (int n = 0; n < 2; ++n) _Pragma("unroll") for (int k = 0; k < 2; ++k) dst[n][k] = *(const LAS bf16x8*)(lds + PG8_SB(b, h) + boff + n * 2048 + k * 1024); } while (0)
; #define PG8_MMA(ai, bj, At, Bt) do { __builtin_amdgcn_s_setprio(1); _Pragma("unroll") for (int m = 0; m < 4; ++m) _Pragma("unroll") for (int n = 0; n < 2; ++n) _Pragma("unroll") for (int k = 0; k < 2; ++k) \
;         acc[ai][bj][m][n] = __builtin_amdgcn_mfma_f32_16x16x32_bf16(Bt[n][k], At[m][k], acc[ai][bj][m][n], 0, 0, 0); __builtin_amdgcn_s_setprio(0); } while (0)
; #define PG8_WAIT_V(n) asm volatile("s_waitcnt vmcnt(" #n ")" ::: "memory")
; #define PG8_WAIT_L(n) asm volatile("s_waitcnt lgkmcnt(" #n ")" ::: "memory")
; #define PG8_BAR __builtin_amdgcn_s_barrier()
; #define PG8_SCHED __builtin_amdgcn_sched_barrier(0)
; template <class Epi, class Sched, bool ALIGN_EPI = true>
; __device__ __forceinline__ void gemm_phase(LAS unsigned char* lds, const Gemm g, const Sched& S, const Epi& E) {
;     ...
;         for (int t = 0; t < nt; t += 2) {
;             const bool last = (t == nt - 2);
;             const char* a1 = cA + (size_t)(t + 1) * kstep;
;             const char* a2 = last ? nA : cA + (size_t)(t + 2) * kstep; const char* b2 = last ? nB : cB + (size_t)(t + 2) * kstep;
;             const char* a3 = a2 + kstep; const char* b3 = b2 + kstep;
;             PG8_LDB(B0, 0, 0); PG8_LDB(B1, 0, 1); PG8_SCHED; PG8_LDA(At, 0, 0); PG8_STAGE(PG8_SA(1, 1), a1 + hsA, voffA);
;             PG8_WAIT_V(8); PG8_WAIT_L(0); PG8_BAR; PG8_MMA(0, 0, At, B0); PG8_MMA(0, 1, At, B1); PG8_BAR; PG8_SCHED;
;             PG8_LDA(At, 0, 1); PG8_STAGE(PG8_SB(0, 0), b2, voffB); PG8_STAGE(PG8_SB(0, 1), b2 + hsB, voffB); PG8_STAGE(PG8_SA(0, 0), a2, voffA);
;             PG8_WAIT_V(8); PG8_WAIT_L(0); PG8_BAR; PG8_MMA(1, 0, At, B0); PG8_MMA(1, 1, At, B1); PG8_BAR; PG8_SCHED;
.LBB0_134:
	ds_read_b128 v[146:149], v158
	ds_read_b128 v[162:165], v158 offset:1024
	ds_read_b128 v[166:169], v158 offset:2048
	ds_read_b128 v[170:173], v158 offset:3072
	ds_read_b128 v[174:177], v159
	ds_read_b128 v[182:185], v159 offset:1024
	ds_read_b128 v[186:189], v159 offset:2048
	ds_read_b128 v[190:193], v159 offset:3072
	s_add_u32 s6, s4, 0xfffc0080
	s_addc_u32 s7, s5, -1
	s_cmp_eq_u32 s58, 12
	s_cselect_b32 s9, s19, s7
	s_cselect_b32 s8, s18, s6
	s_cselect_b32 s7, s3, s33
	s_cselect_b32 s6, s17, s23
	v_lshl_add_u64 v[150:151], s[4:5], 0, v[138:139]
	s_add_i32 m0, s25, 0xc000
	ds_read_b128 v[194:197], v160
	ds_read_b128 v[198:201], v160 offset:1024
	ds_read_b128 v[202:205], v160 offset:2048
	ds_read_b128 v[206:209], v160 offset:3072
	ds_read_b128 v[210:213], v160 offset:4096
	ds_read_b128 v[214:217], v160 offset:5120
	ds_read_b128 v[218:221], v160 offset:6144
	ds_read_b128 v[222:225], v160 offset:7168
	global_load_lds_dwordx4 v[150:151], off
	v_lshl_add_u64 v[150:151], s[4:5], 0, v[140:141]
	s_add_i32 m0, s25, 0xe000
	s_nop 0
	global_load_lds_dwordx4 v[150:151], off
	s_waitcnt vmcnt(8)
	s_waitcnt lgkmcnt(0)
	s_barrier
	s_setprio 1
	s_waitcnt lgkmcnt(0)
	v_mfma_f32_16x16x32_bf16 v[124:127], v[146:149], v[194:197], v[124:127]
	v_mfma_f32_16x16x32_bf16 v[120:123], v[166:169], v[194:197], v[120:123]
	v_mfma_f32_16x16x32_bf16 v[108:111], v[146:149], v[202:205], v[108:111]
	v_mfma_f32_16x16x32_bf16 v[104:107], v[166:169], v[202:205], v[104:107]
	v_mfma_f32_16x16x32_bf16 v[92:95], v[146:149], v[210:213], v[92:95]
	v_mfma_f32_16x16x32_bf16 v[88:91], v[166:169], v[210:213], v[88:91]
	v_mfma_f32_16x16x32_bf16 v[76:79], v[146:149], v[218:221], v[76:79]
	v_mfma_f32_16x16x32_bf16 v[72:75], v[166:169], v[218:221], v[72:75]
	v_mfma_f32_16x16x32_bf16 v[124:127], v[162:165], v[198:201], v[124:127]
	v_mfma_f32_16x16x32_bf16 v[120:123], v[170:173], v[198:201], v[120:123]
	v_mfma_f32_16x16x32_bf16 v[108:111], v[162:165], v[206:209], v[108:111]
	v_mfma_f32_16x16x32_bf16 v[104:107], v[170:173], v[206:209], v[104:107]
	v_mfma_f32_16x16x32_bf16 v[92:95], v[162:165], v[214:217], v[92:95]
	v_mfma_f32_16x16x32_bf16 v[88:91], v[170:173], v[214:217], v[88:91]
	v_mfma_f32_16x16x32_bf16 v[76:79], v[162:165], v[222:225], v[76:79]
	v_mfma_f32_16x16x32_bf16 v[72:75], v[170:173], v[222:225], v[72:75]
	v_mfma_f32_16x16x32_bf16 v[116:119], v[174:177], v[194:197], v[116:119]
	v_mfma_f32_16x16x32_bf16 v[112:115], v[186:189], v[194:197], v[112:115]
	v_mfma_f32_16x16x32_bf16 v[100:103], v[174:177], v[202:205], v[100:103]
	v_mfma_f32_16x16x32_bf16 v[96:99], v[186:189], v[202:205], v[96:99]
	v_mfma_f32_16x16x32_bf16 v[84:87], v[174:177], v[210:213], v[84:87]
	v_mfma_f32_16x16x32_bf16 v[80:83], v[186:189], v[210:213], v[80:83]
	v_mfma_f32_16x16x32_bf16 v[68:71], v[174:177], v[218:221], v[68:71]
	v_mfma_f32_16x16x32_bf16 v[64:67], v[186:189], v[218:221], v[64:67]
	v_mfma_f32_16x16x32_bf16 v[116:119], v[182:185], v[198:201], v[116:119]
	v_mfma_f32_16x16x32_bf16 v[112:115], v[190:193], v[198:201], v[112:115]
	v_mfma_f32_16x16x32_bf16 v[100:103], v[182:185], v[206:209], v[100:103]
	v_mfma_f32_16x16x32_bf16 v[96:99], v[190:193], v[206:209], v[96:99]
	v_mfma_f32_16x16x32_bf16 v[84:87], v[182:185], v[214:217], v[84:87]
	v_mfma_f32_16x16x32_bf16 v[80:83], v[190:193], v[214:217], v[80:83]
	v_mfma_f32_16x16x32_bf16 v[68:71], v[182:185], v[222:225], v[68:71]
	v_mfma_f32_16x16x32_bf16 v[64:67], v[190:193], v[222:225], v[64:67]
	s_setprio 0
	s_barrier
	s_add_i32 s59, s48, s24
	v_lshl_add_u64 v[150:151], s[6:7], 0, v[130:131]
	s_mov_b32 m0, s59
	ds_read_b128 v[194:197], v160 offset:16384
	ds_read_b128 v[198:201], v160 offset:17408
	ds_read_b128 v[202:205], v160 offset:18432
	ds_read_b128 v[206:209], v160 offset:19456
	ds_read_b128 v[210:213], v160 offset:20480
	ds_read_b128 v[214:217], v160 offset:21504
	ds_read_b128 v[218:221], v160 offset:22528
	ds_read_b128 v[222:225], v160 offset:23552
	global_load_lds_dwordx4 v[150:151], off
	s_add_i32 m0, s59, 0x2000
	s_add_u32 s60, s6, 0x40000
	v_lshl_add_u64 v[178:179], s[6:7], 0, v[134:135]
	s_addc_u32 s61, s7, 0
	s_add_i32 s59, s49, s24
	global_load_lds_dwordx4 v[178:179], off
	v_lshl_add_u64 v[226:227], s[60:61], 0, v[130:131]
	s_mov_b32 m0, s59
	v_lshl_add_u64 v[228:229], s[8:9], 0, v[132:133]
	global_load_lds_dwordx4 v[226:227], off
	v_lshl_add_u64 v[226:227], s[60:61], 0, v[134:135]
	s_add_i32 m0, s59, 0x2000
	s_nop 0
	global_load_lds_dwordx4 v[226:227], off
	v_lshl_add_u64 v[226:227], s[8:9], 0, v[128:129]
	s_mov_b32 m0, s25
	s_nop 0
	global_load_lds_dwordx4 v[226:227], off
	s_mov_b32 m0, s26
	s_nop 0
	global_load_lds_dwordx4 v[228:229], off
	s_waitcnt vmcnt(8)
	s_waitcnt lgkmcnt(0)
	s_barrier
; #define PG8_STAGE(bufoff, gbase, voff) do { _Pragma("unroll") for (int _i = 0; _i < 2; ++_i) \
;         __builtin_amdgcn_global_load_lds((const unsigned*)((const char*)(gbase) + (voff)[_i]), (LAS unsigned*)(lds + (bufoff) + ldsw + _i * 8192), 16, 0, 0); } while (0)
; #define PG8_LDA(dst, b, h) do { _Pragma("unroll") for (int m = 0; m < 4; ++m) _Pragma("unroll") for (int k = 0; k < 2; ++k) dst[m][k] = *(const LAS bf16x8*)(lds + PG8_SA(b, h) + aoff + m * 2048 + k * 1024); } while (0)
; #define PG8_LDB(dst, b, h) do { _Pragma("unroll") for (int n = 0; n < 2; ++n) _Pragma("unroll") for (int k = 0; k < 2; ++k) dst[n][k] = *(const LAS bf16x8*)(lds + PG8_SB(b, h) + boff + n * 2048 + k * 1024); } while (0)
; #define PG8_MMA(ai, bj, At, Bt) do { __builtin_amdgcn_s_setprio(1); _Pragma("unroll") for (int m = 0; m < 4; ++m) _Pragma("unroll") for (int n = 0; n < 2; ++n) _Pragma("unroll") for (int k = 0; k < 2; ++k) \
;         acc[ai][bj][m][n] = __builtin_amdgcn_mfma_f32_16x16x32_bf16(Bt[n][k], At[m][k], acc[ai][bj][m][n], 0, 0, 0); __builtin_amdgcn_s_setprio(0); } while (0)
; #define PG8_WAIT_V(n) asm volatile("s_waitcnt vmcnt(" #n ")" ::: "memory")
; #define PG8_WAIT_L(n) asm volatile("s_waitcnt lgkmcnt(" #n ")" ::: "memory")
; #define PG8_BAR __builtin_amdgcn_s_barrier()
; #define PG8_SCHED __builtin_amdgcn_sched_barrier(0)
; template <class Epi, class Sched, bool ALIGN_EPI = true>
; __device__ __forceinline__ void gemm_phase(LAS unsigned char* lds, const Gemm g, const Sched& S, const Epi& E) {
;     ...
;             PG8_WAIT_V(8); PG8_WAIT_L(0); PG8_BAR; PG8_MMA(1, 0, At, B0); PG8_MMA(1, 1, At, B1); PG8_BAR; PG8_SCHED;
;             PG8_LDB(B0, 1, 0); PG8_LDB(B1, 1, 1); PG8_SCHED; PG8_LDA(At, 1, 0); PG8_STAGE(PG8_SA(0, 1), a2 + hsA, voffA);
;             PG8_WAIT_V(8); PG8_WAIT_L(0); PG8_BAR; PG8_MMA(0, 0, At, B0); PG8_MMA(0, 1, At, B1); PG8_BAR; PG8_SCHED;
;             PG8_LDA(At, 1, 1); PG8_STAGE(PG8_SB(1, 0), b3, voffB); PG8_STAGE(PG8_SB(1, 1), b3 + hsB, voffB); PG8_STAGE(PG8_SA(1, 0), a3, voffA);
;             PG8_WAIT_V(8); PG8_WAIT_L(0); PG8_BAR; PG8_MMA(1, 0, At, B0); PG8_MMA(1, 1, At, B1); PG8_BAR; PG8_SCHED;
	s_setprio 1
	s_waitcnt lgkmcnt(0)
	v_mfma_f32_16x16x32_bf16 v[60:63], v[146:149], v[194:197], v[60:63]
	v_mfma_f32_16x16x32_bf16 v[56:59], v[166:169], v[194:197], v[56:59]
	v_mfma_f32_16x16x32_bf16 v[44:47], v[146:149], v[202:205], v[44:47]
	v_mfma_f32_16x16x32_bf16 v[40:43], v[166:169], v[202:205], v[40:43]
	v_mfma_f32_16x16x32_bf16 v[28:31], v[146:149], v[210:213], v[28:31]
	v_mfma_f32_16x16x32_bf16 v[24:27], v[166:169], v[210:213], v[24:27]
	v_mfma_f32_16x16x32_bf16 v[12:15], v[146:149], v[218:221], v[12:15]
	v_mfma_f32_16x16x32_bf16 v[8:11], v[166:169], v[218:221], v[8:11]
	v_mfma_f32_16x16x32_bf16 v[60:63], v[162:165], v[198:201], v[60:63]
	v_mfma_f32_16x16x32_bf16 v[56:59], v[170:173], v[198:201], v[56:59]
	v_mfma_f32_16x16x32_bf16 v[44:47], v[162:165], v[206:209], v[44:47]
	v_mfma_f32_16x16x32_bf16 v[40:43], v[170:173], v[206:209], v[40:43]
	v_mfma_f32_16x16x32_bf16 v[28:31], v[162:165], v[214:217], v[28:31]
	v_mfma_f32_16x16x32_bf16 v[24:27], v[170:173], v[214:217], v[24:27]
	v_mfma_f32_16x16x32_bf16 v[12:15], v[162:165], v[222:225], v[12:15]
	v_mfma_f32_16x16x32_bf16 v[8:11], v[170:173], v[222:225], v[8:11]
	v_mfma_f32_16x16x32_bf16 v[52:55], v[174:177], v[194:197], v[52:55]
	v_mfma_f32_16x16x32_bf16 v[48:51], v[186:189], v[194:197], v[48:51]
	v_mfma_f32_16x16x32_bf16 v[36:39], v[174:177], v[202:205], v[36:39]
	v_mfma_f32_16x16x32_bf16 v[32:35], v[186:189], v[202:205], v[32:35]
	v_mfma_f32_16x16x32_bf16 v[20:23], v[174:177], v[210:213], v[20:23]
	v_mfma_f32_16x16x32_bf16 v[16:19], v[186:189], v[210:213], v[16:19]
	v_mfma_f32_16x16x32_bf16 v[4:7], v[174:177], v[218:221], v[4:7]
	v_mfma_f32_16x16x32_bf16 v[0:3], v[186:189], v[218:221], v[0:3]
	v_mfma_f32_16x16x32_bf16 v[52:55], v[182:185], v[198:201], v[52:55]
	v_mfma_f32_16x16x32_bf16 v[48:51], v[190:193], v[198:201], v[48:51]
	v_mfma_f32_16x16x32_bf16 v[36:39], v[182:185], v[206:209], v[36:39]
	v_mfma_f32_16x16x32_bf16 v[32:35], v[190:193], v[206:209], v[32:35]
	v_mfma_f32_16x16x32_bf16 v[20:23], v[182:185], v[214:217], v[20:23]
	v_mfma_f32_16x16x32_bf16 v[16:19], v[190:193], v[214:217], v[16:19]
	v_mfma_f32_16x16x32_bf16 v[4:7], v[182:185], v[222:225], v[4:7]
	v_mfma_f32_16x16x32_bf16 v[0:3], v[190:193], v[222:225], v[0:3]
	s_setprio 0
	s_barrier
	s_add_i32 s59, 0, 0x18000
	v_add_u32_e32 v136, s59, v156
	s_add_i32 s60, 0, 0x1c000
	ds_read_b128 v[146:149], v136
	ds_read_b128 v[162:165], v136 offset:1024
	ds_read_b128 v[166:169], v136 offset:2048
	ds_read_b128 v[170:173], v136 offset:3072
	v_add_u32_e32 v136, s60, v156
	ds_read_b128 v[174:177], v136
	ds_read_b128 v[182:185], v136 offset:1024
	ds_read_b128 v[186:189], v136 offset:2048
	ds_read_b128 v[190:193], v136 offset:3072
	s_add_u32 s8, s8, 0x40000
	s_addc_u32 s9, s9, 0
	s_mov_b32 m0, s27
	v_lshl_add_u64 v[230:231], s[8:9], 0, v[128:129]
	ds_read_b128 v[194:197], v160 offset:32768
	ds_read_b128 v[198:201], v160 offset:33792
	ds_read_b128 v[202:205], v160 offset:34816
	ds_read_b128 v[206:209], v160 offset:35840
	ds_read_b128 v[210:213], v160 offset:36864
	ds_read_b128 v[214:217], v160 offset:37888
	ds_read_b128 v[218:221], v160 offset:38912
	ds_read_b128 v[222:225], v160 offset:39936
	global_load_lds_dwordx4 v[230:231], off
	v_lshl_add_u64 v[230:231], s[8:9], 0, v[132:133]
	s_mov_b32 m0, s28
	s_nop 0
	global_load_lds_dwordx4 v[230:231], off
	s_waitcnt vmcnt(8)
	s_waitcnt lgkmcnt(0)
	s_barrier
	s_setprio 1
	s_waitcnt lgkmcnt(0)
	v_mfma_f32_16x16x32_bf16 v[124:127], v[146:149], v[194:197], v[124:127]
	v_mfma_f32_16x16x32_bf16 v[120:123], v[166:169], v[194:197], v[120:123]
	v_mfma_f32_16x16x32_bf16 v[108:111], v[146:149], v[202:205], v[108:111]
	v_mfma_f32_16x16x32_bf16 v[104:107], v[166:169], v[202:205], v[104:107]
	v_mfma_f32_16x16x32_bf16 v[92:95], v[146:149], v[210:213], v[92:95]
	v_mfma_f32_16x16x32_bf16 v[88:91], v[166:169], v[210:213], v[88:91]
	v_mfma_f32_16x16x32_bf16 v[76:79], v[146:149], v[218:221], v[76:79]
	v_mfma_f32_16x16x32_bf16 v[72:75], v[166:169], v[218:221], v[72:75]
	v_mfma_f32_16x16x32_bf16 v[124:127], v[162:165], v[198:201], v[124:127]
	v_mfma_f32_16x16x32_bf16 v[120:123], v[170:173], v[198:201], v[120:123]
	v_mfma_f32_16x16x32_bf16 v[108:111], v[162:165], v[206:209], v[108:111]
	v_mfma_f32_16x16x32_bf16 v[104:107], v[170:173], v[206:209], v[104:107]
	v_mfma_f32_16x16x32_bf16 v[92:95], v[162:165], v[214:217], v[92:95]
	v_mfma_f32_16x16x32_bf16 v[88:91], v[170:173], v[214:217], v[88:91]
	v_mfma_f32_16x16x32_bf16 v[76:79], v[162:165], v[222:225], v[76:79]
	v_mfma_f32_16x16x32_bf16 v[72:75], v[170:173], v[222:225], v[72:75]
	v_mfma_f32_16x16x32_bf16 v[116:119], v[174:177], v[194:197], v[116:119]
	v_mfma_f32_16x16x32_bf16 v[112:115], v[186:189], v[194:197], v[112:115]
	v_mfma_f32_16x16x32_bf16 v[100:103], v[174:177], v[202:205], v[100:103]
	v_mfma_f32_16x16x32_bf16 v[96:99], v[186:189], v[202:205], v[96:99]
	v_mfma_f32_16x16x32_bf16 v[84:87], v[174:177], v[210:213], v[84:87]
	v_mfma_f32_16x16x32_bf16 v[80:83], v[186:189], v[210:213], v[80:83]
	v_mfma_f32_16x16x32_bf16 v[68:71], v[174:177], v[218:221], v[68:71]
	v_mfma_f32_16x16x32_bf16 v[64:67], v[186:189], v[218:221], v[64:67]
	v_mfma_f32_16x16x32_bf16 v[116:119], v[182:185], v[198:201], v[116:119]
	v_mfma_f32_16x16x32_bf16 v[112:115], v[190:193], v[198:201], v[112:115]
	v_mfma_f32_16x16x32_bf16 v[100:103], v[182:185], v[206:209], v[100:103]
	v_mfma_f32_16x16x32_bf16 v[96:99], v[190:193], v[206:209], v[96:99]
	v_mfma_f32_16x16x32_bf16 v[84:87], v[182:185], v[214:217], v[84:87]
	v_mfma_f32_16x16x32_bf16 v[80:83], v[190:193], v[214:217], v[80:83]
	v_mfma_f32_16x16x32_bf16 v[68:71], v[182:185], v[222:225], v[68:71]
	v_mfma_f32_16x16x32_bf16 v[64:67], v[190:193], v[222:225], v[64:67]
	s_setprio 0
	s_barrier
; #define PG8_STAGE(bufoff, gbase, voff) do { _Pragma("unroll") for (int _i = 0; _i < 2; ++_i) \
;         __builtin_amdgcn_global_load_lds((const unsigned*)((const char*)(gbase) + (voff)[_i]), (LAS unsigned*)(lds + (bufoff) + ldsw + _i * 8192), 16, 0, 0); } while (0)
; #define PG8_LDA(dst, b, h) do { _Pragma("unroll") for (int m = 0; m < 4; ++m) _Pragma("unroll") for (int k = 0; k < 2; ++k) dst[m][k] = *(const LAS bf16x8*)(lds + PG8_SA(b, h) + aoff + m * 2048 + k * 1024); } while (0)
; #define PG8_MMA(ai, bj, At, Bt) do { __builtin_amdgcn_s_setprio(1); _Pragma("unroll") for (int m = 0; m < 4; ++m) _Pragma("unroll") for (int n = 0; n < 2; ++n) _Pragma("unroll") for (int k = 0; k < 2; ++k) \
;         acc[ai][bj][m][n] = __builtin_amdgcn_mfma_f32_16x16x32_bf16(Bt[n][k], At[m][k], acc[ai][bj][m][n], 0, 0, 0); __builtin_amdgcn_s_setprio(0); } while (0)
; #define PG8_WAIT_V(n) asm volatile("s_waitcnt vmcnt(" #n ")" ::: "memory")
; #define PG8_WAIT_L(n) asm volatile("s_waitcnt lgkmcnt(" #n ")" ::: "memory")
; #define PG8_BAR __builtin_amdgcn_s_barrier()
; #define PG8_SCHED __builtin_amdgcn_sched_barrier(0)
; template <class Epi, class Sched, bool ALIGN_EPI = true>
; __device__ __forceinline__ void gemm_phase(LAS unsigned char* lds, const Gemm g, const Sched& S, const Epi& E) {
;     ...
;             PG8_LDA(At, 1, 1); PG8_STAGE(PG8_SB(1, 0), b3, voffB); PG8_STAGE(PG8_SB(1, 1), b3 + hsB, voffB); PG8_STAGE(PG8_SA(1, 0), a3, voffA);
;             PG8_WAIT_V(8); PG8_WAIT_L(0); PG8_BAR; PG8_MMA(1, 0, At, B0); PG8_MMA(1, 1, At, B1); PG8_BAR; PG8_SCHED;
;         }
;         if constexpr (ALIGN_EPI) { if (wr == 0) PG8_BAR; }
	s_add_i32 s8, s59, s24
	v_lshl_add_u64 v[150:151], v[150:151], 0, s[12:13]
	s_mov_b32 m0, s8
	ds_read_b128 v[194:197], v160 offset:49152
	ds_read_b128 v[198:201], v160 offset:50176
	ds_read_b128 v[202:205], v160 offset:51200
	ds_read_b128 v[206:209], v160 offset:52224
	ds_read_b128 v[210:213], v160 offset:53248
	ds_read_b128 v[214:217], v160 offset:54272
	ds_read_b128 v[218:221], v160 offset:55296
	ds_read_b128 v[222:225], v160 offset:56320
	global_load_lds_dwordx4 v[150:151], off
	s_add_i32 m0, s8, 0x2000
	s_add_u32 s6, s6, 0x40080
	v_lshl_add_u64 v[150:151], v[178:179], 0, s[12:13]
	s_addc_u32 s7, s7, 0
	s_add_i32 s8, s60, s24
	global_load_lds_dwordx4 v[150:151], off
	v_lshl_add_u64 v[150:151], s[6:7], 0, v[130:131]
	s_mov_b32 m0, s8
	s_nop 0
	global_load_lds_dwordx4 v[150:151], off
	v_lshl_add_u64 v[150:151], s[6:7], 0, v[134:135]
	s_add_i32 m0, s8, 0x2000
	s_nop 0
	global_load_lds_dwordx4 v[150:151], off
	v_lshl_add_u64 v[150:151], v[226:227], 0, s[12:13]
	s_mov_b32 m0, s31
	s_nop 0
	global_load_lds_dwordx4 v[150:151], off
	v_lshl_add_u64 v[150:151], v[228:229], 0, s[12:13]
	s_mov_b32 m0, s34
	s_nop 0
	global_load_lds_dwordx4 v[150:151], off
	s_waitcnt vmcnt(8)
	s_waitcnt lgkmcnt(0)
	s_barrier
	s_setprio 1
	s_waitcnt lgkmcnt(0)
	v_mfma_f32_16x16x32_bf16 v[60:63], v[146:149], v[194:197], v[60:63]
	v_mfma_f32_16x16x32_bf16 v[56:59], v[166:169], v[194:197], v[56:59]
	v_mfma_f32_16x16x32_bf16 v[44:47], v[146:149], v[202:205], v[44:47]
	v_mfma_f32_16x16x32_bf16 v[40:43], v[166:169], v[202:205], v[40:43]
	v_mfma_f32_16x16x32_bf16 v[28:31], v[146:149], v[210:213], v[28:31]
	v_mfma_f32_16x16x32_bf16 v[24:27], v[166:169], v[210:213], v[24:27]
	v_mfma_f32_16x16x32_bf16 v[12:15], v[146:149], v[218:221], v[12:15]
	v_mfma_f32_16x16x32_bf16 v[8:11], v[166:169], v[218:221], v[8:11]
	v_mfma_f32_16x16x32_bf16 v[60:63], v[162:165], v[198:201], v[60:63]
	v_mfma_f32_16x16x32_bf16 v[56:59], v[170:173], v[198:201], v[56:59]
	v_mfma_f32_16x16x32_bf16 v[44:47], v[162:165], v[206:209], v[44:47]
	v_mfma_f32_16x16x32_bf16 v[40:43], v[170:173], v[206:209], v[40:43]
	v_mfma_f32_16x16x32_bf16 v[28:31], v[162:165], v[214:217], v[28:31]
	v_mfma_f32_16x16x32_bf16 v[24:27], v[170:173], v[214:217], v[24:27]
	v_mfma_f32_16x16x32_bf16 v[12:15], v[162:165], v[222:225], v[12:15]
	v_mfma_f32_16x16x32_bf16 v[8:11], v[170:173], v[222:225], v[8:11]
	v_mfma_f32_16x16x32_bf16 v[52:55], v[174:177], v[194:197], v[52:55]
	v_mfma_f32_16x16x32_bf16 v[48:51], v[186:189], v[194:197], v[48:51]
	v_mfma_f32_16x16x32_bf16 v[36:39], v[174:177], v[202:205], v[36:39]
	v_mfma_f32_16x16x32_bf16 v[32:35], v[186:189], v[202:205], v[32:35]
	v_mfma_f32_16x16x32_bf16 v[20:23], v[174:177], v[210:213], v[20:23]
	v_mfma_f32_16x16x32_bf16 v[16:19], v[186:189], v[210:213], v[16:19]
	v_mfma_f32_16x16x32_bf16 v[4:7], v[174:177], v[218:221], v[4:7]
	v_mfma_f32_16x16x32_bf16 v[0:3], v[186:189], v[218:221], v[0:3]
	v_mfma_f32_16x16x32_bf16 v[52:55], v[182:185], v[198:201], v[52:55]
	v_mfma_f32_16x16x32_bf16 v[48:51], v[190:193], v[198:201], v[48:51]
	s_add_i32 s58, s58, 2
	v_mfma_f32_16x16x32_bf16 v[36:39], v[182:185], v[206:209], v[36:39]
	s_add_u32 s4, s4, 0x100
	v_mfma_f32_16x16x32_bf16 v[32:35], v[190:193], v[206:209], v[32:35]
	s_addc_u32 s5, s5, 0
	v_mfma_f32_16x16x32_bf16 v[20:23], v[182:185], v[214:217], v[20:23]
	s_add_u32 s23, s23, 0x100
	v_mfma_f32_16x16x32_bf16 v[16:19], v[190:193], v[214:217], v[16:19]
	s_addc_u32 s33, s33, 0
	v_mfma_f32_16x16x32_bf16 v[4:7], v[182:185], v[222:225], v[4:7]
	s_cmp_gt_u32 s58, 13
	v_mfma_f32_16x16x32_bf16 v[0:3], v[190:193], v[222:225], v[0:3]
	s_setprio 0
	s_barrier
	s_cbranch_scc0 .LBB0_134
	s_and_b64 vcc, exec, s[14:15]
	s_cbranch_vccz .LBB0_137
	s_barrier

; #define PG8_STAGE(bufoff, gbase, voff) do { _Pragma("unroll") for (int _i = 0; _i < 2; ++_i) \
;         __builtin_amdgcn_global_load_lds((const unsigned*)((const char*)(gbase) + (voff)[_i]), (LAS unsigned*)(lds + (bufoff) + ldsw + _i * 8192), 16, 0, 0); } while (0)
; #define PG8_LDA(dst, b, h) do { _Pragma("unroll") for (int m = 0; m < 4; ++m) _Pragma("unroll") for (int k = 0; k < 2; ++k) dst[m][k] = *(const LAS bf16x8*)(lds + PG8_SA(b, h) + aoff + m * 2048 + k * 1024); } while (0)
; #define PG8_LDB(dst, b, h) do { _Pragma("unroll") for (int n = 0; n < 2; ++n) _Pragma("unroll") for (int k = 0; k < 2; ++k) dst[n][k] = *(const LAS bf16x8*)(lds + PG8_SB(b, h) + boff + n * 2048 + k * 1024); } while (0)
; #define PG8_MMA(ai, bj, At, Bt) do { __builtin_amdgcn_s_setprio(1); _Pragma("unroll") for (int m = 0; m < 4; ++m) _Pragma("unroll") for (int n = 0; n < 2; ++n) _Pragma("unroll") for (int k = 0; k < 2; ++k) \
;         acc[ai][bj][m][n] = __builtin_amdgcn_mfma_f32_16x16x32_bf16(Bt[n][k], At[m][k], acc[ai][bj][m][n], 0, 0, 0); __builtin_amdgcn_s_setprio(0); } while (0)
; #define PG8_WAIT_V(n) asm volatile("s_waitcnt vmcnt(" #n ")" ::: "memory")
; #define PG8_WAIT_L(n) asm volatile("s_waitcnt lgkmcnt(" #n ")" ::: "memory")
; #define PG8_BAR __builtin_amdgcn_s_barrier()
; #define PG8_SCHED __builtin_amdgcn_sched_barrier(0)
; template <class Epi, class Sched, bool ALIGN_EPI = true>
; __device__ __forceinline__ void gemm_phase(LAS unsigned char* lds, const Gemm g, const Sched& S, const Epi& E) {
;     ...
;         for (int t = 0; t < nt; t += 2) {
;             const bool last = (t == nt - 2);
;             const char* a1 = cA + (size_t)(t + 1) * kstep;
;             const char* a2 = last ? nA : cA + (size_t)(t + 2) * kstep; const char* b2 = last ? nB : cB + (size_t)(t + 2) * kstep;
;             const char* a3 = a2 + kstep; const char* b3 = b2 + kstep;
;             PG8_LDB(B0, 0, 0); PG8_LDB(B1, 0, 1); PG8_SCHED; PG8_LDA(At, 0, 0); PG8_STAGE(PG8_SA(1, 1), a1 + hsA, voffA);
;             PG8_WAIT_V(8); PG8_WAIT_L(0); PG8_BAR; PG8_MMA(0, 0, At, B0); PG8_MMA(0, 1, At, B1); PG8_BAR; PG8_SCHED;
;             PG8_LDA(At, 0, 1); PG8_STAGE(PG8_SB(0, 0), b2, voffB); PG8_STAGE(PG8_SB(0, 1), b2 + hsB, voffB); PG8_STAGE(PG8_SA(0, 0), a2, voffA);
;             PG8_WAIT_V(8); PG8_WAIT_L(0); PG8_BAR; PG8_MMA(1, 0, At, B0); PG8_MMA(1, 1, At, B1); PG8_BAR; PG8_SCHED;
.LBB0_704:
	ds_read_b128 v[144:147], v156
	ds_read_b128 v[148:151], v156 offset:1024
	ds_read_b128 v[160:163], v156 offset:2048
	ds_read_b128 v[164:167], v156 offset:3072
	ds_read_b128 v[168:171], v157
	ds_read_b128 v[172:175], v157 offset:1024
	ds_read_b128 v[176:179], v157 offset:2048
	ds_read_b128 v[182:185], v157 offset:3072
	s_add_u32 s38, s36, 0xfff80080
	s_addc_u32 s39, s37, -1
	s_cmp_eq_u32 s57, 28
	s_cselect_b32 s41, s9, s39
	s_cselect_b32 s40, s27, s38
	s_cselect_b32 s39, s25, s56
	s_cselect_b32 s38, s35, s55
	v_lshl_add_u64 v[218:219], s[36:37], 0, v[136:137]
	s_add_i32 m0, s42, 0xc000
	ds_read_b128 v[186:189], v158
	ds_read_b128 v[190:193], v158 offset:1024
	ds_read_b128 v[194:197], v158 offset:2048
	ds_read_b128 v[198:201], v158 offset:3072
	ds_read_b128 v[202:205], v158 offset:4096
	ds_read_b128 v[206:209], v158 offset:5120
	ds_read_b128 v[210:213], v158 offset:6144
	ds_read_b128 v[214:217], v158 offset:7168
	global_load_lds_dwordx4 v[218:219], off
	v_lshl_add_u64 v[218:219], s[36:37], 0, v[138:139]
	s_add_i32 m0, s42, 0xe000
	s_nop 0
	global_load_lds_dwordx4 v[218:219], off
	s_waitcnt vmcnt(8)
	s_waitcnt lgkmcnt(0)
	s_barrier
	s_setprio 1
	s_waitcnt lgkmcnt(0)
	v_mfma_f32_16x16x32_bf16 v[124:127], v[144:147], v[186:189], v[124:127]
	v_mfma_f32_16x16x32_bf16 v[120:123], v[160:163], v[186:189], v[120:123]
	v_mfma_f32_16x16x32_bf16 v[112:115], v[144:147], v[194:197], v[112:115]
	v_mfma_f32_16x16x32_bf16 v[104:107], v[160:163], v[194:197], v[104:107]
	v_mfma_f32_16x16x32_bf16 v[96:99], v[144:147], v[202:205], v[96:99]
	v_mfma_f32_16x16x32_bf16 v[88:91], v[160:163], v[202:205], v[88:91]
	v_mfma_f32_16x16x32_bf16 v[80:83], v[144:147], v[210:213], v[80:83]
	v_mfma_f32_16x16x32_bf16 v[72:75], v[160:163], v[210:213], v[72:75]
	v_mfma_f32_16x16x32_bf16 v[124:127], v[148:151], v[190:193], v[124:127]
	v_mfma_f32_16x16x32_bf16 v[120:123], v[164:167], v[190:193], v[120:123]
	v_mfma_f32_16x16x32_bf16 v[112:115], v[148:151], v[198:201], v[112:115]
	v_mfma_f32_16x16x32_bf16 v[104:107], v[164:167], v[198:201], v[104:107]
	v_mfma_f32_16x16x32_bf16 v[96:99], v[148:151], v[206:209], v[96:99]
	v_mfma_f32_16x16x32_bf16 v[88:91], v[164:167], v[206:209], v[88:91]
	v_mfma_f32_16x16x32_bf16 v[80:83], v[148:151], v[214:217], v[80:83]
	v_mfma_f32_16x16x32_bf16 v[72:75], v[164:167], v[214:217], v[72:75]
	v_mfma_f32_16x16x32_bf16 v[116:119], v[168:171], v[186:189], v[116:119]
	v_mfma_f32_16x16x32_bf16 v[108:111], v[176:179], v[186:189], v[108:111]
	v_mfma_f32_16x16x32_bf16 v[100:103], v[168:171], v[194:197], v[100:103]
	v_mfma_f32_16x16x32_bf16 v[92:95], v[176:179], v[194:197], v[92:95]
	v_mfma_f32_16x16x32_bf16 v[84:87], v[168:171], v[202:205], v[84:87]
	v_mfma_f32_16x16x32_bf16 v[76:79], v[176:179], v[202:205], v[76:79]
	v_mfma_f32_16x16x32_bf16 v[68:71], v[168:171], v[210:213], v[68:71]
	v_mfma_f32_16x16x32_bf16 v[64:67], v[176:179], v[210:213], v[64:67]
	v_mfma_f32_16x16x32_bf16 v[116:119], v[172:175], v[190:193], v[116:119]
	v_mfma_f32_16x16x32_bf16 v[108:111], v[182:185], v[190:193], v[108:111]
	v_mfma_f32_16x16x32_bf16 v[100:103], v[172:175], v[198:201], v[100:103]
	v_mfma_f32_16x16x32_bf16 v[92:95], v[182:185], v[198:201], v[92:95]
	v_mfma_f32_16x16x32_bf16 v[84:87], v[172:175], v[206:209], v[84:87]
	v_mfma_f32_16x16x32_bf16 v[76:79], v[182:185], v[206:209], v[76:79]
	v_mfma_f32_16x16x32_bf16 v[68:71], v[172:175], v[214:217], v[68:71]
	v_mfma_f32_16x16x32_bf16 v[64:67], v[182:185], v[214:217], v[64:67]
	s_setprio 0
	s_barrier
	s_add_i32 s58, s53, s33
	v_lshl_add_u64 v[218:219], s[38:39], 0, v[130:131]
	s_mov_b32 m0, s58
	ds_read_b128 v[186:189], v158 offset:16384
	ds_read_b128 v[190:193], v158 offset:17408
	ds_read_b128 v[194:197], v158 offset:18432
	ds_read_b128 v[198:201], v158 offset:19456
	ds_read_b128 v[202:205], v158 offset:20480
	ds_read_b128 v[206:209], v158 offset:21504
	ds_read_b128 v[210:213], v158 offset:22528
	ds_read_b128 v[214:217], v158 offset:23552
	global_load_lds_dwordx4 v[218:219], off
	s_add_i32 m0, s58, 0x2000
	s_add_u32 s58, s38, 0x80000
	v_lshl_add_u64 v[220:221], s[38:39], 0, v[134:135]
	s_addc_u32 s59, s39, 0
	s_add_i32 s60, s54, s33
	global_load_lds_dwordx4 v[220:221], off
	v_lshl_add_u64 v[222:223], s[58:59], 0, v[130:131]
	s_mov_b32 m0, s60
	v_lshl_add_u64 v[224:225], s[40:41], 0, v[132:133]
	global_load_lds_dwordx4 v[222:223], off
	v_lshl_add_u64 v[222:223], s[58:59], 0, v[134:135]
	s_add_i32 m0, s60, 0x2000
	s_nop 0
	global_load_lds_dwordx4 v[222:223], off
	v_lshl_add_u64 v[222:223], s[40:41], 0, v[128:129]
	s_mov_b32 m0, s42
	s_nop 0
	global_load_lds_dwordx4 v[222:223], off
	s_mov_b32 m0, s43
	s_nop 0
	global_load_lds_dwordx4 v[224:225], off
	s_waitcnt vmcnt(8)
	s_waitcnt lgkmcnt(0)
	s_barrier
; #define PG8_STAGE(bufoff, gbase, voff) do { _Pragma("unroll") for (int _i = 0; _i < 2; ++_i) \
;         __builtin_amdgcn_global_load_lds((const unsigned*)((const char*)(gbase) + (voff)[_i]), (LAS unsigned*)(lds + (bufoff) + ldsw + _i * 8192), 16, 0, 0); } while (0)
; #define PG8_LDA(dst, b, h) do { _Pragma("unroll") for (int m = 0; m < 4; ++m) _Pragma("unroll") for (int k = 0; k < 2; ++k) dst[m][k] = *(const LAS bf16x8*)(lds + PG8_SA(b, h) + aoff + m * 2048 + k * 1024); } while (0)
; #define PG8_LDB(dst, b, h) do { _Pragma("unroll") for (int n = 0; n < 2; ++n) _Pragma("unroll") for (int k = 0; k < 2; ++k) dst[n][k] = *(const LAS bf16x8*)(lds + PG8_SB(b, h) + boff + n * 2048 + k * 1024); } while (0)
; #define PG8_MMA(ai, bj, At, Bt) do { __builtin_amdgcn_s_setprio(1); _Pragma("unroll") for (int m = 0; m < 4; ++m) _Pragma("unroll") for (int n = 0; n < 2; ++n) _Pragma("unroll") for (int k = 0; k < 2; ++k) \
;         acc[ai][bj][m][n] = __builtin_amdgcn_mfma_f32_16x16x32_bf16(Bt[n][k], At[m][k], acc[ai][bj][m][n], 0, 0, 0); __builtin_amdgcn_s_setprio(0); } while (0)
; #define PG8_WAIT_V(n) asm volatile("s_waitcnt vmcnt(" #n ")" ::: "memory")
; #define PG8_WAIT_L(n) asm volatile("s_waitcnt lgkmcnt(" #n ")" ::: "memory")
; #define PG8_BAR __builtin_amdgcn_s_barrier()
; #define PG8_SCHED __builtin_amdgcn_sched_barrier(0)
; template <class Epi, class Sched, bool ALIGN_EPI = true>
; __device__ __forceinline__ void gemm_phase(LAS unsigned char* lds, const Gemm g, const Sched& S, const Epi& E) {
;     ...
;             PG8_WAIT_V(8); PG8_WAIT_L(0); PG8_BAR; PG8_MMA(1, 0, At, B0); PG8_MMA(1, 1, At, B1); PG8_BAR; PG8_SCHED;
;             PG8_LDB(B0, 1, 0); PG8_LDB(B1, 1, 1); PG8_SCHED; PG8_LDA(At, 1, 0); PG8_STAGE(PG8_SA(0, 1), a2 + hsA, voffA);
;             PG8_WAIT_V(8); PG8_WAIT_L(0); PG8_BAR; PG8_MMA(0, 0, At, B0); PG8_MMA(0, 1, At, B1); PG8_BAR; PG8_SCHED;
;             PG8_LDA(At, 1, 1); PG8_STAGE(PG8_SB(1, 0), b3, voffB); PG8_STAGE(PG8_SB(1, 1), b3 + hsB, voffB); PG8_STAGE(PG8_SA(1, 0), a3, voffA);
;             PG8_WAIT_V(8); PG8_WAIT_L(0); PG8_BAR; PG8_MMA(1, 0, At, B0); PG8_MMA(1, 1, At, B1); PG8_BAR; PG8_SCHED;
	s_setprio 1
	s_waitcnt lgkmcnt(0)
	v_mfma_f32_16x16x32_bf16 v[60:63], v[144:147], v[186:189], v[60:63]
	v_mfma_f32_16x16x32_bf16 v[56:59], v[160:163], v[186:189], v[56:59]
	v_mfma_f32_16x16x32_bf16 v[48:51], v[144:147], v[194:197], v[48:51]
	v_mfma_f32_16x16x32_bf16 v[40:43], v[160:163], v[194:197], v[40:43]
	v_mfma_f32_16x16x32_bf16 v[32:35], v[144:147], v[202:205], v[32:35]
	v_mfma_f32_16x16x32_bf16 v[24:27], v[160:163], v[202:205], v[24:27]
	v_mfma_f32_16x16x32_bf16 v[16:19], v[144:147], v[210:213], v[16:19]
	v_mfma_f32_16x16x32_bf16 v[8:11], v[160:163], v[210:213], v[8:11]
	v_mfma_f32_16x16x32_bf16 v[60:63], v[148:151], v[190:193], v[60:63]
	v_mfma_f32_16x16x32_bf16 v[56:59], v[164:167], v[190:193], v[56:59]
	v_mfma_f32_16x16x32_bf16 v[48:51], v[148:151], v[198:201], v[48:51]
	v_mfma_f32_16x16x32_bf16 v[40:43], v[164:167], v[198:201], v[40:43]
	v_mfma_f32_16x16x32_bf16 v[32:35], v[148:151], v[206:209], v[32:35]
	v_mfma_f32_16x16x32_bf16 v[24:27], v[164:167], v[206:209], v[24:27]
	v_mfma_f32_16x16x32_bf16 v[16:19], v[148:151], v[214:217], v[16:19]
	v_mfma_f32_16x16x32_bf16 v[8:11], v[164:167], v[214:217], v[8:11]
	v_mfma_f32_16x16x32_bf16 v[52:55], v[168:171], v[186:189], v[52:55]
	v_mfma_f32_16x16x32_bf16 v[44:47], v[176:179], v[186:189], v[44:47]
	v_mfma_f32_16x16x32_bf16 v[36:39], v[168:171], v[194:197], v[36:39]
	v_mfma_f32_16x16x32_bf16 v[28:31], v[176:179], v[194:197], v[28:31]
	v_mfma_f32_16x16x32_bf16 v[20:23], v[168:171], v[202:205], v[20:23]
	v_mfma_f32_16x16x32_bf16 v[12:15], v[176:179], v[202:205], v[12:15]
	v_mfma_f32_16x16x32_bf16 v[4:7], v[168:171], v[210:213], v[4:7]
	v_mfma_f32_16x16x32_bf16 v[0:3], v[176:179], v[210:213], v[0:3]
	v_mfma_f32_16x16x32_bf16 v[52:55], v[172:175], v[190:193], v[52:55]
	v_mfma_f32_16x16x32_bf16 v[44:47], v[182:185], v[190:193], v[44:47]
	v_mfma_f32_16x16x32_bf16 v[36:39], v[172:175], v[198:201], v[36:39]
	v_mfma_f32_16x16x32_bf16 v[28:31], v[182:185], v[198:201], v[28:31]
	v_mfma_f32_16x16x32_bf16 v[20:23], v[172:175], v[206:209], v[20:23]
	v_mfma_f32_16x16x32_bf16 v[12:15], v[182:185], v[206:209], v[12:15]
	v_mfma_f32_16x16x32_bf16 v[4:7], v[172:175], v[214:217], v[4:7]
	v_mfma_f32_16x16x32_bf16 v[0:3], v[182:185], v[214:217], v[0:3]
	s_setprio 0
	s_barrier
	s_add_i32 s58, 0, 0x18000
	v_add_u32_e32 v159, s58, v154
	s_add_i32 s59, 0, 0x1c000
	ds_read_b128 v[144:147], v159
	ds_read_b128 v[148:151], v159 offset:1024
	ds_read_b128 v[160:163], v159 offset:2048
	ds_read_b128 v[164:167], v159 offset:3072
	v_add_u32_e32 v159, s59, v154
	ds_read_b128 v[168:171], v159
	ds_read_b128 v[172:175], v159 offset:1024
	ds_read_b128 v[176:179], v159 offset:2048
	ds_read_b128 v[182:185], v159 offset:3072
	s_add_u32 s40, s40, 0x80000
	s_addc_u32 s41, s41, 0
	s_mov_b32 m0, s44
	v_lshl_add_u64 v[226:227], s[40:41], 0, v[128:129]
	ds_read_b128 v[186:189], v158 offset:32768
	ds_read_b128 v[190:193], v158 offset:33792
	ds_read_b128 v[194:197], v158 offset:34816
	ds_read_b128 v[198:201], v158 offset:35840
	ds_read_b128 v[202:205], v158 offset:36864
	ds_read_b128 v[206:209], v158 offset:37888
	ds_read_b128 v[210:213], v158 offset:38912
	ds_read_b128 v[214:217], v158 offset:39936
	global_load_lds_dwordx4 v[226:227], off
	v_lshl_add_u64 v[226:227], s[40:41], 0, v[132:133]
	s_mov_b32 m0, s45
	s_nop 0
	global_load_lds_dwordx4 v[226:227], off
	s_waitcnt vmcnt(8)
	s_waitcnt lgkmcnt(0)
	s_barrier
	s_setprio 1
	s_waitcnt lgkmcnt(0)
	v_mfma_f32_16x16x32_bf16 v[124:127], v[144:147], v[186:189], v[124:127]
	v_mfma_f32_16x16x32_bf16 v[120:123], v[160:163], v[186:189], v[120:123]
	v_mfma_f32_16x16x32_bf16 v[112:115], v[144:147], v[194:197], v[112:115]
	v_mfma_f32_16x16x32_bf16 v[104:107], v[160:163], v[194:197], v[104:107]
	v_mfma_f32_16x16x32_bf16 v[96:99], v[144:147], v[202:205], v[96:99]
	v_mfma_f32_16x16x32_bf16 v[88:91], v[160:163], v[202:205], v[88:91]
	v_mfma_f32_16x16x32_bf16 v[80:83], v[144:147], v[210:213], v[80:83]
	v_mfma_f32_16x16x32_bf16 v[72:75], v[160:163], v[210:213], v[72:75]
	v_mfma_f32_16x16x32_bf16 v[124:127], v[148:151], v[190:193], v[124:127]
	v_mfma_f32_16x16x32_bf16 v[120:123], v[164:167], v[190:193], v[120:123]
	v_mfma_f32_16x16x32_bf16 v[112:115], v[148:151], v[198:201], v[112:115]
	v_mfma_f32_16x16x32_bf16 v[104:107], v[164:167], v[198:201], v[104:107]
	v_mfma_f32_16x16x32_bf16 v[96:99], v[148:151], v[206:209], v[96:99]
	v_mfma_f32_16x16x32_bf16 v[88:91], v[164:167], v[206:209], v[88:91]
	v_mfma_f32_16x16x32_bf16 v[80:83], v[148:151], v[214:217], v[80:83]
	v_mfma_f32_16x16x32_bf16 v[72:75], v[164:167], v[214:217], v[72:75]
	v_mfma_f32_16x16x32_bf16 v[116:119], v[168:171], v[186:189], v[116:119]
	v_mfma_f32_16x16x32_bf16 v[108:111], v[176:179], v[186:189], v[108:111]
	v_mfma_f32_16x16x32_bf16 v[100:103], v[168:171], v[194:197], v[100:103]
	v_mfma_f32_16x16x32_bf16 v[92:95], v[176:179], v[194:197], v[92:95]
	v_mfma_f32_16x16x32_bf16 v[84:87], v[168:171], v[202:205], v[84:87]
	v_mfma_f32_16x16x32_bf16 v[76:79], v[176:179], v[202:205], v[76:79]
	v_mfma_f32_16x16x32_bf16 v[68:71], v[168:171], v[210:213], v[68:71]
	v_mfma_f32_16x16x32_bf16 v[64:67], v[176:179], v[210:213], v[64:67]
	v_mfma_f32_16x16x32_bf16 v[116:119], v[172:175], v[190:193], v[116:119]
	v_mfma_f32_16x16x32_bf16 v[108:111], v[182:185], v[190:193], v[108:111]
	v_mfma_f32_16x16x32_bf16 v[100:103], v[172:175], v[198:201], v[100:103]
	v_mfma_f32_16x16x32_bf16 v[92:95], v[182:185], v[198:201], v[92:95]
	v_mfma_f32_16x16x32_bf16 v[84:87], v[172:175], v[206:209], v[84:87]
	v_mfma_f32_16x16x32_bf16 v[76:79], v[182:185], v[206:209], v[76:79]
	v_mfma_f32_16x16x32_bf16 v[68:71], v[172:175], v[214:217], v[68:71]
	v_mfma_f32_16x16x32_bf16 v[64:67], v[182:185], v[214:217], v[64:67]
	s_setprio 0
	s_barrier
; #define PG8_STAGE(bufoff, gbase, voff) do { _Pragma("unroll") for (int _i = 0; _i < 2; ++_i) \
;         __builtin_amdgcn_global_load_lds((const unsigned*)((const char*)(gbase) + (voff)[_i]), (LAS unsigned*)(lds + (bufoff) + ldsw + _i * 8192), 16, 0, 0); } while (0)
; #define PG8_LDA(dst, b, h) do { _Pragma("unroll") for (int m = 0; m < 4; ++m) _Pragma("unroll") for (int k = 0; k < 2; ++k) dst[m][k] = *(const LAS bf16x8*)(lds + PG8_SA(b, h) + aoff + m * 2048 + k * 1024); } while (0)
; #define PG8_MMA(ai, bj, At, Bt) do { __builtin_amdgcn_s_setprio(1); _Pragma("unroll") for (int m = 0; m < 4; ++m) _Pragma("unroll") for (int n = 0; n < 2; ++n) _Pragma("unroll") for (int k = 0; k < 2; ++k) \
;         acc[ai][bj][m][n] = __builtin_amdgcn_mfma_f32_16x16x32_bf16(Bt[n][k], At[m][k], acc[ai][bj][m][n], 0, 0, 0); __builtin_amdgcn_s_setprio(0); } while (0)
; #define PG8_WAIT_V(n) asm volatile("s_waitcnt vmcnt(" #n ")" ::: "memory")
; #define PG8_WAIT_L(n) asm volatile("s_waitcnt lgkmcnt(" #n ")" ::: "memory")
; #define PG8_BAR __builtin_amdgcn_s_barrier()
; #define PG8_SCHED __builtin_amdgcn_sched_barrier(0)
; template <class Epi, class Sched, bool ALIGN_EPI = true>
; __device__ __forceinline__ void gemm_phase(LAS unsigned char* lds, const Gemm g, const Sched& S, const Epi& E) {
;     ...
;             PG8_LDA(At, 1, 1); PG8_STAGE(PG8_SB(1, 0), b3, voffB); PG8_STAGE(PG8_SB(1, 1), b3 + hsB, voffB); PG8_STAGE(PG8_SA(1, 0), a3, voffA);
;             PG8_WAIT_V(8); PG8_WAIT_L(0); PG8_BAR; PG8_MMA(1, 0, At, B0); PG8_MMA(1, 1, At, B1); PG8_BAR; PG8_SCHED;
;         }
;         if constexpr (ALIGN_EPI) { if (wr == 0) PG8_BAR; }
	s_add_i32 s40, s58, s33
	v_lshl_add_u64 v[218:219], v[218:219], 0, s[12:13]
	s_mov_b32 m0, s40
	ds_read_b128 v[186:189], v158 offset:49152
	ds_read_b128 v[190:193], v158 offset:50176
	ds_read_b128 v[194:197], v158 offset:51200
	ds_read_b128 v[198:201], v158 offset:52224
	ds_read_b128 v[202:205], v158 offset:53248
	ds_read_b128 v[206:209], v158 offset:54272
	ds_read_b128 v[210:213], v158 offset:55296
	ds_read_b128 v[214:217], v158 offset:56320
	global_load_lds_dwordx4 v[218:219], off
	s_add_i32 m0, s40, 0x2000
	s_add_u32 s38, s38, 0x80080
	v_lshl_add_u64 v[218:219], v[220:221], 0, s[12:13]
	s_addc_u32 s39, s39, 0
	s_add_i32 s40, s59, s33
	global_load_lds_dwordx4 v[218:219], off
	v_lshl_add_u64 v[218:219], s[38:39], 0, v[130:131]
	s_mov_b32 m0, s40
	s_nop 0
	global_load_lds_dwordx4 v[218:219], off
	v_lshl_add_u64 v[218:219], s[38:39], 0, v[134:135]
	s_add_i32 m0, s40, 0x2000
	s_nop 0
	global_load_lds_dwordx4 v[218:219], off
	v_lshl_add_u64 v[218:219], v[222:223], 0, s[12:13]
	s_mov_b32 m0, s48
	s_nop 0
	global_load_lds_dwordx4 v[218:219], off
	v_lshl_add_u64 v[218:219], v[224:225], 0, s[12:13]
	s_mov_b32 m0, s49
	s_nop 0
	global_load_lds_dwordx4 v[218:219], off
	s_waitcnt vmcnt(8)
	s_waitcnt lgkmcnt(0)
	s_barrier
	s_setprio 1
	s_waitcnt lgkmcnt(0)
	v_mfma_f32_16x16x32_bf16 v[60:63], v[144:147], v[186:189], v[60:63]
	v_mfma_f32_16x16x32_bf16 v[56:59], v[160:163], v[186:189], v[56:59]
	v_mfma_f32_16x16x32_bf16 v[48:51], v[144:147], v[194:197], v[48:51]
	v_mfma_f32_16x16x32_bf16 v[40:43], v[160:163], v[194:197], v[40:43]
	v_mfma_f32_16x16x32_bf16 v[32:35], v[144:147], v[202:205], v[32:35]
	v_mfma_f32_16x16x32_bf16 v[24:27], v[160:163], v[202:205], v[24:27]
	v_mfma_f32_16x16x32_bf16 v[16:19], v[144:147], v[210:213], v[16:19]
	v_mfma_f32_16x16x32_bf16 v[8:11], v[160:163], v[210:213], v[8:11]
	v_mfma_f32_16x16x32_bf16 v[60:63], v[148:151], v[190:193], v[60:63]
	v_mfma_f32_16x16x32_bf16 v[56:59], v[164:167], v[190:193], v[56:59]
	v_mfma_f32_16x16x32_bf16 v[48:51], v[148:151], v[198:201], v[48:51]
	v_mfma_f32_16x16x32_bf16 v[40:43], v[164:167], v[198:201], v[40:43]
	v_mfma_f32_16x16x32_bf16 v[32:35], v[148:151], v[206:209], v[32:35]
	v_mfma_f32_16x16x32_bf16 v[24:27], v[164:167], v[206:209], v[24:27]
	v_mfma_f32_16x16x32_bf16 v[16:19], v[148:151], v[214:217], v[16:19]
	v_mfma_f32_16x16x32_bf16 v[8:11], v[164:167], v[214:217], v[8:11]
	v_mfma_f32_16x16x32_bf16 v[52:55], v[168:171], v[186:189], v[52:55]
	v_mfma_f32_16x16x32_bf16 v[44:47], v[176:179], v[186:189], v[44:47]
	v_mfma_f32_16x16x32_bf16 v[36:39], v[168:171], v[194:197], v[36:39]
	v_mfma_f32_16x16x32_bf16 v[28:31], v[176:179], v[194:197], v[28:31]
	v_mfma_f32_16x16x32_bf16 v[20:23], v[168:171], v[202:205], v[20:23]
	v_mfma_f32_16x16x32_bf16 v[12:15], v[176:179], v[202:205], v[12:15]
	v_mfma_f32_16x16x32_bf16 v[4:7], v[168:171], v[210:213], v[4:7]
	v_mfma_f32_16x16x32_bf16 v[0:3], v[176:179], v[210:213], v[0:3]
	v_mfma_f32_16x16x32_bf16 v[52:55], v[172:175], v[190:193], v[52:55]
	v_mfma_f32_16x16x32_bf16 v[44:47], v[182:185], v[190:193], v[44:47]
	s_add_i32 s57, s57, 2
	v_mfma_f32_16x16x32_bf16 v[36:39], v[172:175], v[198:201], v[36:39]
	s_add_u32 s36, s36, 0x100
	v_mfma_f32_16x16x32_bf16 v[28:31], v[182:185], v[198:201], v[28:31]
	s_addc_u32 s37, s37, 0
	v_mfma_f32_16x16x32_bf16 v[20:23], v[172:175], v[206:209], v[20:23]
	s_add_u32 s55, s55, 0x100
	v_mfma_f32_16x16x32_bf16 v[12:15], v[182:185], v[206:209], v[12:15]
	s_addc_u32 s56, s56, 0
	v_mfma_f32_16x16x32_bf16 v[4:7], v[172:175], v[214:217], v[4:7]
	s_cmp_gt_u32 s57, 29
	v_mfma_f32_16x16x32_bf16 v[0:3], v[182:185], v[214:217], v[0:3]
	s_setprio 0
	s_barrier
	s_cbranch_scc0 .LBB0_704
	s_and_b64 vcc, exec, s[14:15]
	s_cbranch_vccz .LBB0_707
	s_barrier

; #define PG8_STAGE(bufoff, gbase, voff) do { _Pragma("unroll") for (int _i = 0; _i < 2; ++_i) \
;         __builtin_amdgcn_global_load_lds((const unsigned*)((const char*)(gbase) + (voff)[_i]), (LAS unsigned*)(lds + (bufoff) + ldsw + _i * 8192), 16, 0, 0); } while (0)
; #define PG8_LDA(dst, b, h) do { _Pragma("unroll") for (int m = 0; m < 4; ++m) _Pragma("unroll") for (int k = 0; k < 2; ++k) dst[m][k] = *(const LAS bf16x8*)(lds + PG8_SA(b, h) + aoff + m * 2048 + k * 1024); } while (0)
; #define PG8_LDB(dst, b, h) do { _Pragma("unroll") for (int n = 0; n < 2; ++n) _Pragma("unroll") for (int k = 0; k < 2; ++k) dst[n][k] = *(const LAS bf16x8*)(lds + PG8_SB(b, h) + boff + n * 2048 + k * 1024); } while (0)
; #define PG8_MMA(ai, bj, At, Bt) do { __builtin_amdgcn_s_setprio(1); _Pragma("unroll") for (int m = 0; m < 4; ++m) _Pragma("unroll") for (int n = 0; n < 2; ++n) _Pragma("unroll") for (int k = 0; k < 2; ++k) \
;         acc[ai][bj][m][n] = __builtin_amdgcn_mfma_f32_16x16x32_bf16(Bt[n][k], At[m][k], acc[ai][bj][m][n], 0, 0, 0); __builtin_amdgcn_s_setprio(0); } while (0)
; #define PG8_WAIT_V(n) asm volatile("s_waitcnt vmcnt(" #n ")" ::: "memory")
; #define PG8_WAIT_L(n) asm volatile("s_waitcnt lgkmcnt(" #n ")" ::: "memory")
; #define PG8_BAR __builtin_amdgcn_s_barrier()
; #define PG8_SCHED __builtin_amdgcn_sched_barrier(0)
; template <class Epi, class Sched, bool ALIGN_EPI = true>
; __device__ __forceinline__ void gemm_phase(LAS unsigned char* lds, const Gemm g, const Sched& S, const Epi& E) {
;     ...
;         for (int t = 0; t < nt; t += 2) {
;             const bool last = (t == nt - 2);
;             const char* a1 = cA + (size_t)(t + 1) * kstep;
;             const char* a2 = last ? nA : cA + (size_t)(t + 2) * kstep; const char* b2 = last ? nB : cB + (size_t)(t + 2) * kstep;
;             const char* a3 = a2 + kstep; const char* b3 = b2 + kstep;
;             PG8_LDB(B0, 0, 0); PG8_LDB(B1, 0, 1); PG8_SCHED; PG8_LDA(At, 0, 0); PG8_STAGE(PG8_SA(1, 1), a1 + hsA, voffA);
;             PG8_WAIT_V(8); PG8_WAIT_L(0); PG8_BAR; PG8_MMA(0, 0, At, B0); PG8_MMA(0, 1, At, B1); PG8_BAR; PG8_SCHED;
;             PG8_LDA(At, 0, 1); PG8_STAGE(PG8_SB(0, 0), b2, voffB); PG8_STAGE(PG8_SB(0, 1), b2 + hsB, voffB); PG8_STAGE(PG8_SA(0, 0), a2, voffA);
;             PG8_WAIT_V(8); PG8_WAIT_L(0); PG8_BAR; PG8_MMA(1, 0, At, B0); PG8_MMA(1, 1, At, B1); PG8_BAR; PG8_SCHED;
.LBB0_881:
	ds_read_b128 v[116:119], v184
	ds_read_b128 v[120:123], v184 offset:1024
	ds_read_b128 v[128:131], v184 offset:2048
	ds_read_b128 v[132:135], v184 offset:3072
	ds_read_b128 v[144:147], v185
	ds_read_b128 v[148:151], v185 offset:1024
	ds_read_b128 v[170:173], v185 offset:2048
	ds_read_b128 v[174:177], v185 offset:3072
	s_add_u32 s26, s6, 0xfffc0080
	s_addc_u32 s27, s7, -1
	s_cmp_eq_u32 s35, 12
	s_cselect_b32 s29, s23, s27
	s_cselect_b32 s28, s22, s26
	s_cselect_b32 s27, s9, s34
	s_cselect_b32 s26, s21, s31
	v_lshl_add_u64 v[178:179], s[6:7], 0, v[162:163]
	s_add_i32 m0, s42, 0xc000
	ds_read_b128 v[188:191], v186
	ds_read_b128 v[192:195], v186 offset:1024
	ds_read_b128 v[196:199], v186 offset:2048
	ds_read_b128 v[200:203], v186 offset:3072
	ds_read_b128 v[204:207], v186 offset:4096
	ds_read_b128 v[208:211], v186 offset:5120
	ds_read_b128 v[212:215], v186 offset:6144
	ds_read_b128 v[216:219], v186 offset:7168
	global_load_lds_dwordx4 v[178:179], off
	v_lshl_add_u64 v[178:179], s[6:7], 0, v[164:165]
	s_add_i32 m0, s42, 0xe000
	s_nop 0
	global_load_lds_dwordx4 v[178:179], off
	s_waitcnt vmcnt(8)
	s_waitcnt lgkmcnt(0)
	s_barrier
	s_setprio 1
	s_waitcnt lgkmcnt(0)
	v_mfma_f32_16x16x32_bf16 v[140:143], v[116:119], v[188:191], v[140:143]
	v_mfma_f32_16x16x32_bf16 v[64:67], v[128:131], v[188:191], v[64:67]
	v_mfma_f32_16x16x32_bf16 v[124:127], v[116:119], v[196:199], v[124:127]
	v_mfma_f32_16x16x32_bf16 v[52:55], v[128:131], v[196:199], v[52:55]
	v_mfma_f32_16x16x32_bf16 v[108:111], v[116:119], v[204:207], v[108:111]
	v_mfma_f32_16x16x32_bf16 v[44:47], v[128:131], v[204:207], v[44:47]
	v_mfma_f32_16x16x32_bf16 v[100:103], v[116:119], v[212:215], v[100:103]
	v_mfma_f32_16x16x32_bf16 v[36:39], v[128:131], v[212:215], v[36:39]
	v_mfma_f32_16x16x32_bf16 v[140:143], v[120:123], v[192:195], v[140:143]
	v_mfma_f32_16x16x32_bf16 v[64:67], v[132:135], v[192:195], v[64:67]
	v_mfma_f32_16x16x32_bf16 v[124:127], v[120:123], v[200:203], v[124:127]
	v_mfma_f32_16x16x32_bf16 v[52:55], v[132:135], v[200:203], v[52:55]
	v_mfma_f32_16x16x32_bf16 v[108:111], v[120:123], v[208:211], v[108:111]
	v_mfma_f32_16x16x32_bf16 v[44:47], v[132:135], v[208:211], v[44:47]
	v_mfma_f32_16x16x32_bf16 v[100:103], v[120:123], v[216:219], v[100:103]
	v_mfma_f32_16x16x32_bf16 v[36:39], v[132:135], v[216:219], v[36:39]
	v_mfma_f32_16x16x32_bf16 v[136:139], v[144:147], v[188:191], v[136:139]
	v_mfma_f32_16x16x32_bf16 v[56:59], v[170:173], v[188:191], v[56:59]
	v_mfma_f32_16x16x32_bf16 v[112:115], v[144:147], v[196:199], v[112:115]
	v_mfma_f32_16x16x32_bf16 v[48:51], v[170:173], v[196:199], v[48:51]
	v_mfma_f32_16x16x32_bf16 v[104:107], v[144:147], v[204:207], v[104:107]
	v_mfma_f32_16x16x32_bf16 v[40:43], v[170:173], v[204:207], v[40:43]
	v_mfma_f32_16x16x32_bf16 v[96:99], v[144:147], v[212:215], v[96:99]
	v_mfma_f32_16x16x32_bf16 v[32:35], v[170:173], v[212:215], v[32:35]
	v_mfma_f32_16x16x32_bf16 v[136:139], v[148:151], v[192:195], v[136:139]
	v_mfma_f32_16x16x32_bf16 v[56:59], v[174:177], v[192:195], v[56:59]
	v_mfma_f32_16x16x32_bf16 v[112:115], v[148:151], v[200:203], v[112:115]
	v_mfma_f32_16x16x32_bf16 v[48:51], v[174:177], v[200:203], v[48:51]
	v_mfma_f32_16x16x32_bf16 v[104:107], v[148:151], v[208:211], v[104:107]
	v_mfma_f32_16x16x32_bf16 v[40:43], v[174:177], v[208:211], v[40:43]
	v_mfma_f32_16x16x32_bf16 v[96:99], v[148:151], v[216:219], v[96:99]
	v_mfma_f32_16x16x32_bf16 v[32:35], v[174:177], v[216:219], v[32:35]
	s_setprio 0
	s_barrier
	s_add_i32 s36, s62, s33
	v_lshl_add_u64 v[178:179], s[26:27], 0, v[156:157]
	s_mov_b32 m0, s36
	ds_read_b128 v[188:191], v186 offset:16384
	ds_read_b128 v[192:195], v186 offset:17408
	ds_read_b128 v[196:199], v186 offset:18432
	ds_read_b128 v[200:203], v186 offset:19456
	ds_read_b128 v[204:207], v186 offset:20480
	ds_read_b128 v[208:211], v186 offset:21504
	ds_read_b128 v[212:215], v186 offset:22528
	ds_read_b128 v[216:219], v186 offset:23552
	global_load_lds_dwordx4 v[178:179], off
	s_add_i32 m0, s36, 0x2000
	s_add_u32 s36, s26, 0x40000
	v_lshl_add_u64 v[220:221], s[26:27], 0, v[160:161]
	s_addc_u32 s37, s27, 0
	s_add_i32 s38, s63, s33
	global_load_lds_dwordx4 v[220:221], off
	v_lshl_add_u64 v[222:223], s[36:37], 0, v[156:157]
	s_mov_b32 m0, s38
	v_lshl_add_u64 v[224:225], s[28:29], 0, v[158:159]
	global_load_lds_dwordx4 v[222:223], off
	v_lshl_add_u64 v[222:223], s[36:37], 0, v[160:161]
	s_add_i32 m0, s38, 0x2000
	s_nop 0
	global_load_lds_dwordx4 v[222:223], off
	v_lshl_add_u64 v[222:223], s[28:29], 0, v[154:155]
	s_mov_b32 m0, s42
	s_nop 0
	global_load_lds_dwordx4 v[222:223], off
	s_mov_b32 m0, s43
	s_nop 0
	global_load_lds_dwordx4 v[224:225], off
	s_waitcnt vmcnt(8)
	s_waitcnt lgkmcnt(0)
	s_barrier
; #define PG8_STAGE(bufoff, gbase, voff) do { _Pragma("unroll") for (int _i = 0; _i < 2; ++_i) \
;         __builtin_amdgcn_global_load_lds((const unsigned*)((const char*)(gbase) + (voff)[_i]), (LAS unsigned*)(lds + (bufoff) + ldsw + _i * 8192), 16, 0, 0); } while (0)
; #define PG8_LDA(dst, b, h) do { _Pragma("unroll") for (int m = 0; m < 4; ++m) _Pragma("unroll") for (int k = 0; k < 2; ++k) dst[m][k] = *(const LAS bf16x8*)(lds + PG8_SA(b, h) + aoff + m * 2048 + k * 1024); } while (0)
; #define PG8_LDB(dst, b, h) do { _Pragma("unroll") for (int n = 0; n < 2; ++n) _Pragma("unroll") for (int k = 0; k < 2; ++k) dst[n][k] = *(const LAS bf16x8*)(lds + PG8_SB(b, h) + boff + n * 2048 + k * 1024); } while (0)
; #define PG8_MMA(ai, bj, At, Bt) do { __builtin_amdgcn_s_setprio(1); _Pragma("unroll") for (int m = 0; m < 4; ++m) _Pragma("unroll") for (int n = 0; n < 2; ++n) _Pragma("unroll") for (int k = 0; k < 2; ++k) \
;         acc[ai][bj][m][n] = __builtin_amdgcn_mfma_f32_16x16x32_bf16(Bt[n][k], At[m][k], acc[ai][bj][m][n], 0, 0, 0); __builtin_amdgcn_s_setprio(0); } while (0)
; #define PG8_WAIT_V(n) asm volatile("s_waitcnt vmcnt(" #n ")" ::: "memory")
; #define PG8_WAIT_L(n) asm volatile("s_waitcnt lgkmcnt(" #n ")" ::: "memory")
; #define PG8_BAR __builtin_amdgcn_s_barrier()
; #define PG8_SCHED __builtin_amdgcn_sched_barrier(0)
; template <class Epi, class Sched, bool ALIGN_EPI = true>
; __device__ __forceinline__ void gemm_phase(LAS unsigned char* lds, const Gemm g, const Sched& S, const Epi& E) {
;     ...
;             PG8_WAIT_V(8); PG8_WAIT_L(0); PG8_BAR; PG8_MMA(1, 0, At, B0); PG8_MMA(1, 1, At, B1); PG8_BAR; PG8_SCHED;
;             PG8_LDB(B0, 1, 0); PG8_LDB(B1, 1, 1); PG8_SCHED; PG8_LDA(At, 1, 0); PG8_STAGE(PG8_SA(0, 1), a2 + hsA, voffA);
;             PG8_WAIT_V(8); PG8_WAIT_L(0); PG8_BAR; PG8_MMA(0, 0, At, B0); PG8_MMA(0, 1, At, B1); PG8_BAR; PG8_SCHED;
;             PG8_LDA(At, 1, 1); PG8_STAGE(PG8_SB(1, 0), b3, voffB); PG8_STAGE(PG8_SB(1, 1), b3 + hsB, voffB); PG8_STAGE(PG8_SA(1, 0), a3, voffA);
;             PG8_WAIT_V(8); PG8_WAIT_L(0); PG8_BAR; PG8_MMA(1, 0, At, B0); PG8_MMA(1, 1, At, B1); PG8_BAR; PG8_SCHED;
	s_setprio 1
	s_waitcnt lgkmcnt(0)
	v_mfma_f32_16x16x32_bf16 v[92:95], v[116:119], v[188:191], v[92:95]
	v_mfma_f32_16x16x32_bf16 v[28:31], v[128:131], v[188:191], v[28:31]
	v_mfma_f32_16x16x32_bf16 v[84:87], v[116:119], v[196:199], v[84:87]
	v_mfma_f32_16x16x32_bf16 v[20:23], v[128:131], v[196:199], v[20:23]
	v_mfma_f32_16x16x32_bf16 v[76:79], v[116:119], v[204:207], v[76:79]
	v_mfma_f32_16x16x32_bf16 v[12:15], v[128:131], v[204:207], v[12:15]
	v_mfma_f32_16x16x32_bf16 v[68:71], v[116:119], v[212:215], v[68:71]
	v_mfma_f32_16x16x32_bf16 v[4:7], v[128:131], v[212:215], v[4:7]
	v_mfma_f32_16x16x32_bf16 v[92:95], v[120:123], v[192:195], v[92:95]
	v_mfma_f32_16x16x32_bf16 v[28:31], v[132:135], v[192:195], v[28:31]
	v_mfma_f32_16x16x32_bf16 v[84:87], v[120:123], v[200:203], v[84:87]
	v_mfma_f32_16x16x32_bf16 v[20:23], v[132:135], v[200:203], v[20:23]
	v_mfma_f32_16x16x32_bf16 v[76:79], v[120:123], v[208:211], v[76:79]
	v_mfma_f32_16x16x32_bf16 v[12:15], v[132:135], v[208:211], v[12:15]
	v_mfma_f32_16x16x32_bf16 v[68:71], v[120:123], v[216:219], v[68:71]
	v_mfma_f32_16x16x32_bf16 v[4:7], v[132:135], v[216:219], v[4:7]
	v_mfma_f32_16x16x32_bf16 v[88:91], v[144:147], v[188:191], v[88:91]
	v_mfma_f32_16x16x32_bf16 v[24:27], v[170:173], v[188:191], v[24:27]
	v_mfma_f32_16x16x32_bf16 v[80:83], v[144:147], v[196:199], v[80:83]
	v_mfma_f32_16x16x32_bf16 v[16:19], v[170:173], v[196:199], v[16:19]
	v_mfma_f32_16x16x32_bf16 v[72:75], v[144:147], v[204:207], v[72:75]
	v_mfma_f32_16x16x32_bf16 v[8:11], v[170:173], v[204:207], v[8:11]
	v_mfma_f32_16x16x32_bf16 v[60:63], v[144:147], v[212:215], v[60:63]
	v_mfma_f32_16x16x32_bf16 v[0:3], v[170:173], v[212:215], v[0:3]
	v_mfma_f32_16x16x32_bf16 v[88:91], v[148:151], v[192:195], v[88:91]
	v_mfma_f32_16x16x32_bf16 v[24:27], v[174:177], v[192:195], v[24:27]
	v_mfma_f32_16x16x32_bf16 v[80:83], v[148:151], v[200:203], v[80:83]
	v_mfma_f32_16x16x32_bf16 v[16:19], v[174:177], v[200:203], v[16:19]
	v_mfma_f32_16x16x32_bf16 v[72:75], v[148:151], v[208:211], v[72:75]
	v_mfma_f32_16x16x32_bf16 v[8:11], v[174:177], v[208:211], v[8:11]
	v_mfma_f32_16x16x32_bf16 v[60:63], v[148:151], v[216:219], v[60:63]
	v_mfma_f32_16x16x32_bf16 v[0:3], v[174:177], v[216:219], v[0:3]
	s_setprio 0
	s_barrier
	s_add_i32 s36, 0, 0x18000
	s_add_i32 s37, 0, 0x1c000
	v_add_u32_e32 v132, s36, v182
	v_add_u32_e32 v174, s37, v182
	ds_read_b128 v[116:119], v132
	ds_read_b128 v[120:123], v132 offset:1024
	ds_read_b128 v[128:131], v132 offset:2048
	ds_read_b128 v[132:135], v132 offset:3072
	ds_read_b128 v[144:147], v174
	ds_read_b128 v[148:151], v174 offset:1024
	ds_read_b128 v[170:173], v174 offset:2048
	ds_read_b128 v[174:177], v174 offset:3072
	s_add_u32 s28, s28, 0x40000
	s_addc_u32 s29, s29, 0
	s_mov_b32 m0, s44
	v_lshl_add_u64 v[226:227], s[28:29], 0, v[154:155]
	ds_read_b128 v[188:191], v186 offset:32768
	ds_read_b128 v[192:195], v186 offset:33792
	ds_read_b128 v[196:199], v186 offset:34816
	ds_read_b128 v[200:203], v186 offset:35840
	ds_read_b128 v[204:207], v186 offset:36864
	ds_read_b128 v[208:211], v186 offset:37888
	ds_read_b128 v[212:215], v186 offset:38912
	ds_read_b128 v[216:219], v186 offset:39936
	global_load_lds_dwordx4 v[226:227], off
	v_lshl_add_u64 v[226:227], s[28:29], 0, v[158:159]
	s_mov_b32 m0, s45
	s_nop 0
	global_load_lds_dwordx4 v[226:227], off
	s_waitcnt vmcnt(8)
	s_waitcnt lgkmcnt(0)
	s_barrier
	s_setprio 1
	s_waitcnt lgkmcnt(0)
	v_mfma_f32_16x16x32_bf16 v[140:143], v[116:119], v[188:191], v[140:143]
	v_mfma_f32_16x16x32_bf16 v[64:67], v[128:131], v[188:191], v[64:67]
	v_mfma_f32_16x16x32_bf16 v[124:127], v[116:119], v[196:199], v[124:127]
	v_mfma_f32_16x16x32_bf16 v[52:55], v[128:131], v[196:199], v[52:55]
	v_mfma_f32_16x16x32_bf16 v[108:111], v[116:119], v[204:207], v[108:111]
	v_mfma_f32_16x16x32_bf16 v[44:47], v[128:131], v[204:207], v[44:47]
	v_mfma_f32_16x16x32_bf16 v[100:103], v[116:119], v[212:215], v[100:103]
	v_mfma_f32_16x16x32_bf16 v[36:39], v[128:131], v[212:215], v[36:39]
	v_mfma_f32_16x16x32_bf16 v[140:143], v[120:123], v[192:195], v[140:143]
	v_mfma_f32_16x16x32_bf16 v[64:67], v[132:135], v[192:195], v[64:67]
	v_mfma_f32_16x16x32_bf16 v[124:127], v[120:123], v[200:203], v[124:127]
	v_mfma_f32_16x16x32_bf16 v[52:55], v[132:135], v[200:203], v[52:55]
	v_mfma_f32_16x16x32_bf16 v[108:111], v[120:123], v[208:211], v[108:111]
	v_mfma_f32_16x16x32_bf16 v[44:47], v[132:135], v[208:211], v[44:47]
	v_mfma_f32_16x16x32_bf16 v[100:103], v[120:123], v[216:219], v[100:103]
	v_mfma_f32_16x16x32_bf16 v[36:39], v[132:135], v[216:219], v[36:39]
	v_mfma_f32_16x16x32_bf16 v[136:139], v[144:147], v[188:191], v[136:139]
	v_mfma_f32_16x16x32_bf16 v[56:59], v[170:173], v[188:191], v[56:59]
	v_mfma_f32_16x16x32_bf16 v[112:115], v[144:147], v[196:199], v[112:115]
	v_mfma_f32_16x16x32_bf16 v[48:51], v[170:173], v[196:199], v[48:51]
	v_mfma_f32_16x16x32_bf16 v[104:107], v[144:147], v[204:207], v[104:107]
	v_mfma_f32_16x16x32_bf16 v[40:43], v[170:173], v[204:207], v[40:43]
	v_mfma_f32_16x16x32_bf16 v[96:99], v[144:147], v[212:215], v[96:99]
	v_mfma_f32_16x16x32_bf16 v[32:35], v[170:173], v[212:215], v[32:35]
	v_mfma_f32_16x16x32_bf16 v[136:139], v[148:151], v[192:195], v[136:139]
	v_mfma_f32_16x16x32_bf16 v[56:59], v[174:177], v[192:195], v[56:59]
	v_mfma_f32_16x16x32_bf16 v[112:115], v[148:151], v[200:203], v[112:115]
	v_mfma_f32_16x16x32_bf16 v[48:51], v[174:177], v[200:203], v[48:51]
	v_mfma_f32_16x16x32_bf16 v[104:107], v[148:151], v[208:211], v[104:107]
	v_mfma_f32_16x16x32_bf16 v[40:43], v[174:177], v[208:211], v[40:43]
	v_mfma_f32_16x16x32_bf16 v[96:99], v[148:151], v[216:219], v[96:99]
	v_mfma_f32_16x16x32_bf16 v[32:35], v[174:177], v[216:219], v[32:35]
	s_setprio 0
	s_barrier
; #define PG8_STAGE(bufoff, gbase, voff) do { _Pragma("unroll") for (int _i = 0; _i < 2; ++_i) \
;         __builtin_amdgcn_global_load_lds((const unsigned*)((const char*)(gbase) + (voff)[_i]), (LAS unsigned*)(lds + (bufoff) + ldsw + _i * 8192), 16, 0, 0); } while (0)
; #define PG8_LDA(dst, b, h) do { _Pragma("unroll") for (int m = 0; m < 4; ++m) _Pragma("unroll") for (int k = 0; k < 2; ++k) dst[m][k] = *(const LAS bf16x8*)(lds + PG8_SA(b, h) + aoff + m * 2048 + k * 1024); } while (0)
; #define PG8_MMA(ai, bj, At, Bt) do { __builtin_amdgcn_s_setprio(1); _Pragma("unroll") for (int m = 0; m < 4; ++m) _Pragma("unroll") for (int n = 0; n < 2; ++n) _Pragma("unroll") for (int k = 0; k < 2; ++k) \
;         acc[ai][bj][m][n] = __builtin_amdgcn_mfma_f32_16x16x32_bf16(Bt[n][k], At[m][k], acc[ai][bj][m][n], 0, 0, 0); __builtin_amdgcn_s_setprio(0); } while (0)
; #define PG8_WAIT_V(n) asm volatile("s_waitcnt vmcnt(" #n ")" ::: "memory")
; #define PG8_WAIT_L(n) asm volatile("s_waitcnt lgkmcnt(" #n ")" ::: "memory")
; #define PG8_BAR __builtin_amdgcn_s_barrier()
; #define PG8_SCHED __builtin_amdgcn_sched_barrier(0)
; template <class Epi, class Sched, bool ALIGN_EPI = true>
; __device__ __forceinline__ void gemm_phase(LAS unsigned char* lds, const Gemm g, const Sched& S, const Epi& E) {
;     ...
;             PG8_LDA(At, 1, 1); PG8_STAGE(PG8_SB(1, 0), b3, voffB); PG8_STAGE(PG8_SB(1, 1), b3 + hsB, voffB); PG8_STAGE(PG8_SA(1, 0), a3, voffA);
;             PG8_WAIT_V(8); PG8_WAIT_L(0); PG8_BAR; PG8_MMA(1, 0, At, B0); PG8_MMA(1, 1, At, B1); PG8_BAR; PG8_SCHED;
;         }
;         if constexpr (ALIGN_EPI) { if (wr == 0) PG8_BAR; }
	s_add_i32 s28, s36, s33
	v_lshl_add_u64 v[178:179], v[178:179], 0, s[94:95]
	s_mov_b32 m0, s28
	ds_read_b128 v[188:191], v186 offset:49152
	ds_read_b128 v[192:195], v186 offset:50176
	ds_read_b128 v[196:199], v186 offset:51200
	ds_read_b128 v[200:203], v186 offset:52224
	ds_read_b128 v[204:207], v186 offset:53248
	ds_read_b128 v[208:211], v186 offset:54272
	ds_read_b128 v[212:215], v186 offset:55296
	ds_read_b128 v[216:219], v186 offset:56320
	global_load_lds_dwordx4 v[178:179], off
	s_add_i32 m0, s28, 0x2000
	s_add_u32 s26, s26, 0x40080
	v_lshl_add_u64 v[178:179], v[220:221], 0, s[94:95]
	s_addc_u32 s27, s27, 0
	s_add_i32 s28, s37, s33
	global_load_lds_dwordx4 v[178:179], off
	v_lshl_add_u64 v[178:179], s[26:27], 0, v[156:157]
	s_mov_b32 m0, s28
	s_nop 0
	global_load_lds_dwordx4 v[178:179], off
	v_lshl_add_u64 v[178:179], s[26:27], 0, v[160:161]
	s_add_i32 m0, s28, 0x2000
	s_nop 0
	global_load_lds_dwordx4 v[178:179], off
	v_lshl_add_u64 v[178:179], v[222:223], 0, s[94:95]
	s_mov_b32 m0, s48
	s_nop 0
	global_load_lds_dwordx4 v[178:179], off
	v_lshl_add_u64 v[178:179], v[224:225], 0, s[94:95]
	s_mov_b32 m0, s49
	s_nop 0
	global_load_lds_dwordx4 v[178:179], off
	s_waitcnt vmcnt(8)
	s_waitcnt lgkmcnt(0)
	s_barrier
	s_setprio 1
	s_waitcnt lgkmcnt(0)
	v_mfma_f32_16x16x32_bf16 v[92:95], v[116:119], v[188:191], v[92:95]
	v_mfma_f32_16x16x32_bf16 v[28:31], v[128:131], v[188:191], v[28:31]
	v_mfma_f32_16x16x32_bf16 v[84:87], v[116:119], v[196:199], v[84:87]
	v_mfma_f32_16x16x32_bf16 v[20:23], v[128:131], v[196:199], v[20:23]
	v_mfma_f32_16x16x32_bf16 v[76:79], v[116:119], v[204:207], v[76:79]
	v_mfma_f32_16x16x32_bf16 v[12:15], v[128:131], v[204:207], v[12:15]
	v_mfma_f32_16x16x32_bf16 v[68:71], v[116:119], v[212:215], v[68:71]
	v_mfma_f32_16x16x32_bf16 v[4:7], v[128:131], v[212:215], v[4:7]
	v_mfma_f32_16x16x32_bf16 v[92:95], v[120:123], v[192:195], v[92:95]
	v_mfma_f32_16x16x32_bf16 v[28:31], v[132:135], v[192:195], v[28:31]
	v_mfma_f32_16x16x32_bf16 v[84:87], v[120:123], v[200:203], v[84:87]
	v_mfma_f32_16x16x32_bf16 v[20:23], v[132:135], v[200:203], v[20:23]
	v_mfma_f32_16x16x32_bf16 v[76:79], v[120:123], v[208:211], v[76:79]
	v_mfma_f32_16x16x32_bf16 v[12:15], v[132:135], v[208:211], v[12:15]
	v_mfma_f32_16x16x32_bf16 v[68:71], v[120:123], v[216:219], v[68:71]
	v_mfma_f32_16x16x32_bf16 v[4:7], v[132:135], v[216:219], v[4:7]
	v_mfma_f32_16x16x32_bf16 v[88:91], v[144:147], v[188:191], v[88:91]
	v_mfma_f32_16x16x32_bf16 v[24:27], v[170:173], v[188:191], v[24:27]
	v_mfma_f32_16x16x32_bf16 v[80:83], v[144:147], v[196:199], v[80:83]
	v_mfma_f32_16x16x32_bf16 v[16:19], v[170:173], v[196:199], v[16:19]
	v_mfma_f32_16x16x32_bf16 v[72:75], v[144:147], v[204:207], v[72:75]
	v_mfma_f32_16x16x32_bf16 v[8:11], v[170:173], v[204:207], v[8:11]
	v_mfma_f32_16x16x32_bf16 v[60:63], v[144:147], v[212:215], v[60:63]
	v_mfma_f32_16x16x32_bf16 v[0:3], v[170:173], v[212:215], v[0:3]
	v_mfma_f32_16x16x32_bf16 v[88:91], v[148:151], v[192:195], v[88:91]
	v_mfma_f32_16x16x32_bf16 v[24:27], v[174:177], v[192:195], v[24:27]
	s_add_i32 s35, s35, 2
	v_mfma_f32_16x16x32_bf16 v[80:83], v[148:151], v[200:203], v[80:83]
	s_add_u32 s6, s6, 0x100
	v_mfma_f32_16x16x32_bf16 v[16:19], v[174:177], v[200:203], v[16:19]
	s_addc_u32 s7, s7, 0
	v_mfma_f32_16x16x32_bf16 v[72:75], v[148:151], v[208:211], v[72:75]
	s_add_u32 s31, s31, 0x100
	v_mfma_f32_16x16x32_bf16 v[8:11], v[174:177], v[208:211], v[8:11]
	s_addc_u32 s34, s34, 0
	v_mfma_f32_16x16x32_bf16 v[60:63], v[148:151], v[216:219], v[60:63]
	s_cmp_gt_u32 s35, 13
	v_mfma_f32_16x16x32_bf16 v[0:3], v[174:177], v[216:219], v[0:3]
	s_setprio 0
	s_barrier
	s_cbranch_scc0 .LBB0_881
	s_and_b64 vcc, exec, s[96:97]
	s_cbranch_vccz .LBB0_884
	s_barrier

; #define PG8_STAGE(bufoff, gbase, voff) do { _Pragma("unroll") for (int _i = 0; _i < 2; ++_i) \
;         __builtin_amdgcn_global_load_lds((const unsigned*)((const char*)(gbase) + (voff)[_i]), (LAS unsigned*)(lds + (bufoff) + ldsw + _i * 8192), 16, 0, 0); } while (0)
; #define PG8_LDA(dst, b, h) do { _Pragma("unroll") for (int m = 0; m < 4; ++m) _Pragma("unroll") for (int k = 0; k < 2; ++k) dst[m][k] = *(const LAS bf16x8*)(lds + PG8_SA(b, h) + aoff + m * 2048 + k * 1024); } while (0)
; #define PG8_LDB(dst, b, h) do { _Pragma("unroll") for (int n = 0; n < 2; ++n) _Pragma("unroll") for (int k = 0; k < 2; ++k) dst[n][k] = *(const LAS bf16x8*)(lds + PG8_SB(b, h) + boff + n * 2048 + k * 1024); } while (0)
; #define PG8_MMA(ai, bj, At, Bt) do { __builtin_amdgcn_s_setprio(1); _Pragma("unroll") for (int m = 0; m < 4; ++m) _Pragma("unroll") for (int n = 0; n < 2; ++n) _Pragma("unroll") for (int k = 0; k < 2; ++k) \
;         acc[ai][bj][m][n] = __builtin_amdgcn_mfma_f32_16x16x32_bf16(Bt[n][k], At[m][k], acc[ai][bj][m][n], 0, 0, 0); __builtin_amdgcn_s_setprio(0); } while (0)
; #define PG8_WAIT_V(n) asm volatile("s_waitcnt vmcnt(" #n ")" ::: "memory")
; #define PG8_WAIT_L(n) asm volatile("s_waitcnt lgkmcnt(" #n ")" ::: "memory")
; #define PG8_BAR __builtin_amdgcn_s_barrier()
; #define PG8_SCHED __builtin_amdgcn_sched_barrier(0)
; template <class Epi, class Sched, bool ALIGN_EPI = true>
; __device__ __forceinline__ void gemm_phase(LAS unsigned char* lds, const Gemm g, const Sched& S, const Epi& E) {
;     ...
;         for (int t = 0; t < nt; t += 2) {
;             const bool last = (t == nt - 2);
;             const char* a1 = cA + (size_t)(t + 1) * kstep;
;             const char* a2 = last ? nA : cA + (size_t)(t + 2) * kstep; const char* b2 = last ? nB : cB + (size_t)(t + 2) * kstep;
;             const char* a3 = a2 + kstep; const char* b3 = b2 + kstep;
;             PG8_LDB(B0, 0, 0); PG8_LDB(B1, 0, 1); PG8_SCHED; PG8_LDA(At, 0, 0); PG8_STAGE(PG8_SA(1, 1), a1 + hsA, voffA);
;             PG8_WAIT_V(8); PG8_WAIT_L(0); PG8_BAR; PG8_MMA(0, 0, At, B0); PG8_MMA(0, 1, At, B1); PG8_BAR; PG8_SCHED;
;             PG8_LDA(At, 0, 1); PG8_STAGE(PG8_SB(0, 0), b2, voffB); PG8_STAGE(PG8_SB(0, 1), b2 + hsB, voffB); PG8_STAGE(PG8_SA(0, 0), a2, voffA);
;             PG8_WAIT_V(8); PG8_WAIT_L(0); PG8_BAR; PG8_MMA(1, 0, At, B0); PG8_MMA(1, 1, At, B1); PG8_BAR; PG8_SCHED;
.LBB0_999:
	ds_read_b128 v[144:147], v156
	ds_read_b128 v[148:151], v156 offset:1024
	ds_read_b128 v[160:163], v156 offset:2048
	ds_read_b128 v[164:167], v156 offset:3072
	ds_read_b128 v[168:171], v157
	ds_read_b128 v[172:175], v157 offset:1024
	ds_read_b128 v[176:179], v157 offset:2048
	ds_read_b128 v[182:185], v157 offset:3072
	s_add_u32 s4, s26, 0x100
	s_addc_u32 s5, s27, 0
	s_cmp_eq_u32 s53, 40
	s_cselect_b32 s31, s23, s5
	s_cselect_b32 s30, s22, s4
	s_cselect_b32 s29, s25, s52
	s_cselect_b32 s28, s24, s51
	v_lshl_add_u64 v[218:219], s[26:27], 0, v[136:137]
	s_add_i32 m0, s34, 0xc000
	ds_read_b128 v[186:189], v158
	ds_read_b128 v[190:193], v158 offset:1024
	ds_read_b128 v[194:197], v158 offset:2048
	ds_read_b128 v[198:201], v158 offset:3072
	ds_read_b128 v[202:205], v158 offset:4096
	ds_read_b128 v[206:209], v158 offset:5120
	ds_read_b128 v[210:213], v158 offset:6144
	ds_read_b128 v[214:217], v158 offset:7168
	global_load_lds_dwordx4 v[218:219], off
	v_lshl_add_u64 v[218:219], s[26:27], 0, v[138:139]
	s_add_i32 m0, s34, 0xe000
	s_nop 0
	global_load_lds_dwordx4 v[218:219], off
	s_waitcnt vmcnt(8)
	s_waitcnt lgkmcnt(0)
	s_barrier
	s_setprio 1
	s_waitcnt lgkmcnt(0)
	v_mfma_f32_16x16x32_bf16 v[124:127], v[144:147], v[186:189], v[124:127]
	v_mfma_f32_16x16x32_bf16 v[120:123], v[160:163], v[186:189], v[120:123]
	v_mfma_f32_16x16x32_bf16 v[112:115], v[144:147], v[194:197], v[112:115]
	v_mfma_f32_16x16x32_bf16 v[104:107], v[160:163], v[194:197], v[104:107]
	v_mfma_f32_16x16x32_bf16 v[96:99], v[144:147], v[202:205], v[96:99]
	v_mfma_f32_16x16x32_bf16 v[88:91], v[160:163], v[202:205], v[88:91]
	v_mfma_f32_16x16x32_bf16 v[80:83], v[144:147], v[210:213], v[80:83]
	v_mfma_f32_16x16x32_bf16 v[72:75], v[160:163], v[210:213], v[72:75]
	v_mfma_f32_16x16x32_bf16 v[124:127], v[148:151], v[190:193], v[124:127]
	v_mfma_f32_16x16x32_bf16 v[120:123], v[164:167], v[190:193], v[120:123]
	v_mfma_f32_16x16x32_bf16 v[112:115], v[148:151], v[198:201], v[112:115]
	v_mfma_f32_16x16x32_bf16 v[104:107], v[164:167], v[198:201], v[104:107]
	v_mfma_f32_16x16x32_bf16 v[96:99], v[148:151], v[206:209], v[96:99]
	v_mfma_f32_16x16x32_bf16 v[88:91], v[164:167], v[206:209], v[88:91]
	v_mfma_f32_16x16x32_bf16 v[80:83], v[148:151], v[214:217], v[80:83]
	v_mfma_f32_16x16x32_bf16 v[72:75], v[164:167], v[214:217], v[72:75]
	v_mfma_f32_16x16x32_bf16 v[116:119], v[168:171], v[186:189], v[116:119]
	v_mfma_f32_16x16x32_bf16 v[108:111], v[176:179], v[186:189], v[108:111]
	v_mfma_f32_16x16x32_bf16 v[100:103], v[168:171], v[194:197], v[100:103]
	v_mfma_f32_16x16x32_bf16 v[92:95], v[176:179], v[194:197], v[92:95]
	v_mfma_f32_16x16x32_bf16 v[84:87], v[168:171], v[202:205], v[84:87]
	v_mfma_f32_16x16x32_bf16 v[76:79], v[176:179], v[202:205], v[76:79]
	v_mfma_f32_16x16x32_bf16 v[68:71], v[168:171], v[210:213], v[68:71]
	v_mfma_f32_16x16x32_bf16 v[64:67], v[176:179], v[210:213], v[64:67]
	v_mfma_f32_16x16x32_bf16 v[116:119], v[172:175], v[190:193], v[116:119]
	v_mfma_f32_16x16x32_bf16 v[108:111], v[182:185], v[190:193], v[108:111]
	v_mfma_f32_16x16x32_bf16 v[100:103], v[172:175], v[198:201], v[100:103]
	v_mfma_f32_16x16x32_bf16 v[92:95], v[182:185], v[198:201], v[92:95]
	v_mfma_f32_16x16x32_bf16 v[84:87], v[172:175], v[206:209], v[84:87]
	v_mfma_f32_16x16x32_bf16 v[76:79], v[182:185], v[206:209], v[76:79]
	v_mfma_f32_16x16x32_bf16 v[68:71], v[172:175], v[214:217], v[68:71]
	v_mfma_f32_16x16x32_bf16 v[64:67], v[182:185], v[214:217], v[64:67]
	s_setprio 0
	s_barrier
	s_add_i32 s26, s45, s33
	v_lshl_add_u64 v[218:219], s[28:29], 0, v[130:131]
	s_mov_b32 m0, s26
	ds_read_b128 v[186:189], v158 offset:16384
	ds_read_b128 v[190:193], v158 offset:17408
	ds_read_b128 v[194:197], v158 offset:18432
	ds_read_b128 v[198:201], v158 offset:19456
	ds_read_b128 v[202:205], v158 offset:20480
	ds_read_b128 v[206:209], v158 offset:21504
	ds_read_b128 v[210:213], v158 offset:22528
	ds_read_b128 v[214:217], v158 offset:23552
	global_load_lds_dwordx4 v[218:219], off
	s_add_i32 m0, s26, 0x2000
	s_add_u32 s26, s28, 0xb0000
	v_lshl_add_u64 v[220:221], s[28:29], 0, v[134:135]
	s_addc_u32 s27, s29, 0
	s_add_i32 s54, s46, s33
	global_load_lds_dwordx4 v[220:221], off
	v_lshl_add_u64 v[222:223], s[26:27], 0, v[130:131]
	s_mov_b32 m0, s54
	v_lshl_add_u64 v[224:225], s[30:31], 0, v[132:133]
	global_load_lds_dwordx4 v[222:223], off
	v_lshl_add_u64 v[222:223], s[26:27], 0, v[134:135]
	s_add_i32 m0, s54, 0x2000
	s_nop 0
	global_load_lds_dwordx4 v[222:223], off
	v_lshl_add_u64 v[222:223], s[30:31], 0, v[128:129]
	s_mov_b32 m0, s34
	s_nop 0
	global_load_lds_dwordx4 v[222:223], off
	s_mov_b32 m0, s35
	s_nop 0
	global_load_lds_dwordx4 v[224:225], off
	s_waitcnt vmcnt(8)
	s_waitcnt lgkmcnt(0)
	s_barrier
; #define PG8_STAGE(bufoff, gbase, voff) do { _Pragma("unroll") for (int _i = 0; _i < 2; ++_i) \
;         __builtin_amdgcn_global_load_lds((const unsigned*)((const char*)(gbase) + (voff)[_i]), (LAS unsigned*)(lds + (bufoff) + ldsw + _i * 8192), 16, 0, 0); } while (0)
; #define PG8_LDA(dst, b, h) do { _Pragma("unroll") for (int m = 0; m < 4; ++m) _Pragma("unroll") for (int k = 0; k < 2; ++k) dst[m][k] = *(const LAS bf16x8*)(lds + PG8_SA(b, h) + aoff + m * 2048 + k * 1024); } while (0)
; #define PG8_LDB(dst, b, h) do { _Pragma("unroll") for (int n = 0; n < 2; ++n) _Pragma("unroll") for (int k = 0; k < 2; ++k) dst[n][k] = *(const LAS bf16x8*)(lds + PG8_SB(b, h) + boff + n * 2048 + k * 1024); } while (0)
; #define PG8_MMA(ai, bj, At, Bt) do { __builtin_amdgcn_s_setprio(1); _Pragma("unroll") for (int m = 0; m < 4; ++m) _Pragma("unroll") for (int n = 0; n < 2; ++n) _Pragma("unroll") for (int k = 0; k < 2; ++k) \
;         acc[ai][bj][m][n] = __builtin_amdgcn_mfma_f32_16x16x32_bf16(Bt[n][k], At[m][k], acc[ai][bj][m][n], 0, 0, 0); __builtin_amdgcn_s_setprio(0); } while (0)
; #define PG8_WAIT_V(n) asm volatile("s_waitcnt vmcnt(" #n ")" ::: "memory")
; #define PG8_WAIT_L(n) asm volatile("s_waitcnt lgkmcnt(" #n ")" ::: "memory")
; #define PG8_BAR __builtin_amdgcn_s_barrier()
; #define PG8_SCHED __builtin_amdgcn_sched_barrier(0)
; template <class Epi, class Sched, bool ALIGN_EPI = true>
; __device__ __forceinline__ void gemm_phase(LAS unsigned char* lds, const Gemm g, const Sched& S, const Epi& E) {
;     ...
;             PG8_WAIT_V(8); PG8_WAIT_L(0); PG8_BAR; PG8_MMA(1, 0, At, B0); PG8_MMA(1, 1, At, B1); PG8_BAR; PG8_SCHED;
;             PG8_LDB(B0, 1, 0); PG8_LDB(B1, 1, 1); PG8_SCHED; PG8_LDA(At, 1, 0); PG8_STAGE(PG8_SA(0, 1), a2 + hsA, voffA);
;             PG8_WAIT_V(8); PG8_WAIT_L(0); PG8_BAR; PG8_MMA(0, 0, At, B0); PG8_MMA(0, 1, At, B1); PG8_BAR; PG8_SCHED;
;             PG8_LDA(At, 1, 1); PG8_STAGE(PG8_SB(1, 0), b3, voffB); PG8_STAGE(PG8_SB(1, 1), b3 + hsB, voffB); PG8_STAGE(PG8_SA(1, 0), a3, voffA);
;             PG8_WAIT_V(8); PG8_WAIT_L(0); PG8_BAR; PG8_MMA(1, 0, At, B0); PG8_MMA(1, 1, At, B1); PG8_BAR; PG8_SCHED;
	s_setprio 1
	s_waitcnt lgkmcnt(0)
	v_mfma_f32_16x16x32_bf16 v[60:63], v[144:147], v[186:189], v[60:63]
	v_mfma_f32_16x16x32_bf16 v[56:59], v[160:163], v[186:189], v[56:59]
	v_mfma_f32_16x16x32_bf16 v[48:51], v[144:147], v[194:197], v[48:51]
	v_mfma_f32_16x16x32_bf16 v[40:43], v[160:163], v[194:197], v[40:43]
	v_mfma_f32_16x16x32_bf16 v[32:35], v[144:147], v[202:205], v[32:35]
	v_mfma_f32_16x16x32_bf16 v[24:27], v[160:163], v[202:205], v[24:27]
	v_mfma_f32_16x16x32_bf16 v[16:19], v[144:147], v[210:213], v[16:19]
	v_mfma_f32_16x16x32_bf16 v[8:11], v[160:163], v[210:213], v[8:11]
	v_mfma_f32_16x16x32_bf16 v[60:63], v[148:151], v[190:193], v[60:63]
	v_mfma_f32_16x16x32_bf16 v[56:59], v[164:167], v[190:193], v[56:59]
	v_mfma_f32_16x16x32_bf16 v[48:51], v[148:151], v[198:201], v[48:51]
	v_mfma_f32_16x16x32_bf16 v[40:43], v[164:167], v[198:201], v[40:43]
	v_mfma_f32_16x16x32_bf16 v[32:35], v[148:151], v[206:209], v[32:35]
	v_mfma_f32_16x16x32_bf16 v[24:27], v[164:167], v[206:209], v[24:27]
	v_mfma_f32_16x16x32_bf16 v[16:19], v[148:151], v[214:217], v[16:19]
	v_mfma_f32_16x16x32_bf16 v[8:11], v[164:167], v[214:217], v[8:11]
	v_mfma_f32_16x16x32_bf16 v[52:55], v[168:171], v[186:189], v[52:55]
	v_mfma_f32_16x16x32_bf16 v[44:47], v[176:179], v[186:189], v[44:47]
	v_mfma_f32_16x16x32_bf16 v[36:39], v[168:171], v[194:197], v[36:39]
	v_mfma_f32_16x16x32_bf16 v[28:31], v[176:179], v[194:197], v[28:31]
	v_mfma_f32_16x16x32_bf16 v[20:23], v[168:171], v[202:205], v[20:23]
	v_mfma_f32_16x16x32_bf16 v[12:15], v[176:179], v[202:205], v[12:15]
	v_mfma_f32_16x16x32_bf16 v[4:7], v[168:171], v[210:213], v[4:7]
	v_mfma_f32_16x16x32_bf16 v[0:3], v[176:179], v[210:213], v[0:3]
	v_mfma_f32_16x16x32_bf16 v[52:55], v[172:175], v[190:193], v[52:55]
	v_mfma_f32_16x16x32_bf16 v[44:47], v[182:185], v[190:193], v[44:47]
	v_mfma_f32_16x16x32_bf16 v[36:39], v[172:175], v[198:201], v[36:39]
	v_mfma_f32_16x16x32_bf16 v[28:31], v[182:185], v[198:201], v[28:31]
	v_mfma_f32_16x16x32_bf16 v[20:23], v[172:175], v[206:209], v[20:23]
	v_mfma_f32_16x16x32_bf16 v[12:15], v[182:185], v[206:209], v[12:15]
	v_mfma_f32_16x16x32_bf16 v[4:7], v[172:175], v[214:217], v[4:7]
	v_mfma_f32_16x16x32_bf16 v[0:3], v[182:185], v[214:217], v[0:3]
	s_setprio 0
	s_barrier
	s_add_i32 s54, 0, 0x18000
	v_add_u32_e32 v159, s54, v154
	s_add_i32 s55, 0, 0x1c000
	ds_read_b128 v[144:147], v159
	ds_read_b128 v[148:151], v159 offset:1024
	ds_read_b128 v[160:163], v159 offset:2048
	ds_read_b128 v[164:167], v159 offset:3072
	v_add_u32_e32 v159, s55, v154
	ds_read_b128 v[168:171], v159
	ds_read_b128 v[172:175], v159 offset:1024
	ds_read_b128 v[176:179], v159 offset:2048
	ds_read_b128 v[182:185], v159 offset:3072
	s_add_u32 s26, s30, 0xb0000
	s_addc_u32 s27, s31, 0
	s_mov_b32 m0, s36
	v_lshl_add_u64 v[226:227], s[26:27], 0, v[128:129]
	ds_read_b128 v[186:189], v158 offset:32768
	ds_read_b128 v[190:193], v158 offset:33792
	ds_read_b128 v[194:197], v158 offset:34816
	ds_read_b128 v[198:201], v158 offset:35840
	ds_read_b128 v[202:205], v158 offset:36864
	ds_read_b128 v[206:209], v158 offset:37888
	ds_read_b128 v[210:213], v158 offset:38912
	ds_read_b128 v[214:217], v158 offset:39936
	global_load_lds_dwordx4 v[226:227], off
	v_lshl_add_u64 v[226:227], s[26:27], 0, v[132:133]
	s_mov_b32 m0, s37
	s_nop 0
	global_load_lds_dwordx4 v[226:227], off
	s_waitcnt vmcnt(8)
	s_waitcnt lgkmcnt(0)
	s_barrier
	s_setprio 1
	s_waitcnt lgkmcnt(0)
	v_mfma_f32_16x16x32_bf16 v[124:127], v[144:147], v[186:189], v[124:127]
	v_mfma_f32_16x16x32_bf16 v[120:123], v[160:163], v[186:189], v[120:123]
	v_mfma_f32_16x16x32_bf16 v[112:115], v[144:147], v[194:197], v[112:115]
	v_mfma_f32_16x16x32_bf16 v[104:107], v[160:163], v[194:197], v[104:107]
	v_mfma_f32_16x16x32_bf16 v[96:99], v[144:147], v[202:205], v[96:99]
	v_mfma_f32_16x16x32_bf16 v[88:91], v[160:163], v[202:205], v[88:91]
	v_mfma_f32_16x16x32_bf16 v[80:83], v[144:147], v[210:213], v[80:83]
	v_mfma_f32_16x16x32_bf16 v[72:75], v[160:163], v[210:213], v[72:75]
	v_mfma_f32_16x16x32_bf16 v[124:127], v[148:151], v[190:193], v[124:127]
	v_mfma_f32_16x16x32_bf16 v[120:123], v[164:167], v[190:193], v[120:123]
	v_mfma_f32_16x16x32_bf16 v[112:115], v[148:151], v[198:201], v[112:115]
	v_mfma_f32_16x16x32_bf16 v[104:107], v[164:167], v[198:201], v[104:107]
	v_mfma_f32_16x16x32_bf16 v[96:99], v[148:151], v[206:209], v[96:99]
	v_mfma_f32_16x16x32_bf16 v[88:91], v[164:167], v[206:209], v[88:91]
	v_mfma_f32_16x16x32_bf16 v[80:83], v[148:151], v[214:217], v[80:83]
	v_mfma_f32_16x16x32_bf16 v[72:75], v[164:167], v[214:217], v[72:75]
	v_mfma_f32_16x16x32_bf16 v[116:119], v[168:171], v[186:189], v[116:119]
	v_mfma_f32_16x16x32_bf16 v[108:111], v[176:179], v[186:189], v[108:111]
	v_mfma_f32_16x16x32_bf16 v[100:103], v[168:171], v[194:197], v[100:103]
	v_mfma_f32_16x16x32_bf16 v[92:95], v[176:179], v[194:197], v[92:95]
	v_mfma_f32_16x16x32_bf16 v[84:87], v[168:171], v[202:205], v[84:87]
	v_mfma_f32_16x16x32_bf16 v[76:79], v[176:179], v[202:205], v[76:79]
	v_mfma_f32_16x16x32_bf16 v[68:71], v[168:171], v[210:213], v[68:71]
	v_mfma_f32_16x16x32_bf16 v[64:67], v[176:179], v[210:213], v[64:67]
	v_mfma_f32_16x16x32_bf16 v[116:119], v[172:175], v[190:193], v[116:119]
	v_mfma_f32_16x16x32_bf16 v[108:111], v[182:185], v[190:193], v[108:111]
	v_mfma_f32_16x16x32_bf16 v[100:103], v[172:175], v[198:201], v[100:103]
	v_mfma_f32_16x16x32_bf16 v[92:95], v[182:185], v[198:201], v[92:95]
	v_mfma_f32_16x16x32_bf16 v[84:87], v[172:175], v[206:209], v[84:87]
	v_mfma_f32_16x16x32_bf16 v[76:79], v[182:185], v[206:209], v[76:79]
	v_mfma_f32_16x16x32_bf16 v[68:71], v[172:175], v[214:217], v[68:71]
	v_mfma_f32_16x16x32_bf16 v[64:67], v[182:185], v[214:217], v[64:67]
	s_setprio 0
	s_barrier
; #define PG8_STAGE(bufoff, gbase, voff) do { _Pragma("unroll") for (int _i = 0; _i < 2; ++_i) \
;         __builtin_amdgcn_global_load_lds((const unsigned*)((const char*)(gbase) + (voff)[_i]), (LAS unsigned*)(lds + (bufoff) + ldsw + _i * 8192), 16, 0, 0); } while (0)
; #define PG8_LDA(dst, b, h) do { _Pragma("unroll") for (int m = 0; m < 4; ++m) _Pragma("unroll") for (int k = 0; k < 2; ++k) dst[m][k] = *(const LAS bf16x8*)(lds + PG8_SA(b, h) + aoff + m * 2048 + k * 1024); } while (0)
; #define PG8_MMA(ai, bj, At, Bt) do { __builtin_amdgcn_s_setprio(1); _Pragma("unroll") for (int m = 0; m < 4; ++m) _Pragma("unroll") for (int n = 0; n < 2; ++n) _Pragma("unroll") for (int k = 0; k < 2; ++k) \
;         acc[ai][bj][m][n] = __builtin_amdgcn_mfma_f32_16x16x32_bf16(Bt[n][k], At[m][k], acc[ai][bj][m][n], 0, 0, 0); __builtin_amdgcn_s_setprio(0); } while (0)
; #define PG8_WAIT_V(n) asm volatile("s_waitcnt vmcnt(" #n ")" ::: "memory")
; #define PG8_WAIT_L(n) asm volatile("s_waitcnt lgkmcnt(" #n ")" ::: "memory")
; #define PG8_BAR __builtin_amdgcn_s_barrier()
; #define PG8_SCHED __builtin_amdgcn_sched_barrier(0)
; template <class Epi, class Sched, bool ALIGN_EPI = true>
; __device__ __forceinline__ void gemm_phase(LAS unsigned char* lds, const Gemm g, const Sched& S, const Epi& E) {
;     ...
;             PG8_LDA(At, 1, 1); PG8_STAGE(PG8_SB(1, 0), b3, voffB); PG8_STAGE(PG8_SB(1, 1), b3 + hsB, voffB); PG8_STAGE(PG8_SA(1, 0), a3, voffA);
;             PG8_WAIT_V(8); PG8_WAIT_L(0); PG8_BAR; PG8_MMA(1, 0, At, B0); PG8_MMA(1, 1, At, B1); PG8_BAR; PG8_SCHED;
;         }
;         if constexpr (ALIGN_EPI) { if (wr == 0) PG8_BAR; }
	s_add_i32 s26, s54, s33
	v_lshl_add_u64 v[218:219], v[218:219], 0, s[8:9]
	s_mov_b32 m0, s26
	ds_read_b128 v[186:189], v158 offset:49152
	ds_read_b128 v[190:193], v158 offset:50176
	ds_read_b128 v[194:197], v158 offset:51200
	ds_read_b128 v[198:201], v158 offset:52224
	ds_read_b128 v[202:205], v158 offset:53248
	ds_read_b128 v[206:209], v158 offset:54272
	ds_read_b128 v[210:213], v158 offset:55296
	ds_read_b128 v[214:217], v158 offset:56320
	global_load_lds_dwordx4 v[218:219], off
	s_add_i32 m0, s26, 0x2000
	s_add_u32 s26, s28, 0xb0080
	v_lshl_add_u64 v[218:219], v[220:221], 0, s[8:9]
	s_addc_u32 s27, s29, 0
	s_add_i32 s28, s55, s33
	global_load_lds_dwordx4 v[218:219], off
	v_lshl_add_u64 v[218:219], s[26:27], 0, v[130:131]
	s_mov_b32 m0, s28
	s_nop 0
	global_load_lds_dwordx4 v[218:219], off
	v_lshl_add_u64 v[218:219], s[26:27], 0, v[134:135]
	s_add_i32 m0, s28, 0x2000
	s_nop 0
	global_load_lds_dwordx4 v[218:219], off
	v_lshl_add_u64 v[218:219], v[222:223], 0, s[8:9]
	s_mov_b32 m0, s40
	s_nop 0
	global_load_lds_dwordx4 v[218:219], off
	v_lshl_add_u64 v[218:219], v[224:225], 0, s[8:9]
	s_mov_b32 m0, s41
	s_nop 0
	global_load_lds_dwordx4 v[218:219], off
	s_waitcnt vmcnt(8)
	s_waitcnt lgkmcnt(0)
	s_barrier
	s_setprio 1
	s_waitcnt lgkmcnt(0)
	v_mfma_f32_16x16x32_bf16 v[60:63], v[144:147], v[186:189], v[60:63]
	v_mfma_f32_16x16x32_bf16 v[56:59], v[160:163], v[186:189], v[56:59]
	v_mfma_f32_16x16x32_bf16 v[48:51], v[144:147], v[194:197], v[48:51]
	v_mfma_f32_16x16x32_bf16 v[40:43], v[160:163], v[194:197], v[40:43]
	v_mfma_f32_16x16x32_bf16 v[32:35], v[144:147], v[202:205], v[32:35]
	v_mfma_f32_16x16x32_bf16 v[24:27], v[160:163], v[202:205], v[24:27]
	v_mfma_f32_16x16x32_bf16 v[16:19], v[144:147], v[210:213], v[16:19]
	v_mfma_f32_16x16x32_bf16 v[8:11], v[160:163], v[210:213], v[8:11]
	v_mfma_f32_16x16x32_bf16 v[60:63], v[148:151], v[190:193], v[60:63]
	v_mfma_f32_16x16x32_bf16 v[56:59], v[164:167], v[190:193], v[56:59]
	v_mfma_f32_16x16x32_bf16 v[48:51], v[148:151], v[198:201], v[48:51]
	v_mfma_f32_16x16x32_bf16 v[40:43], v[164:167], v[198:201], v[40:43]
	v_mfma_f32_16x16x32_bf16 v[32:35], v[148:151], v[206:209], v[32:35]
	v_mfma_f32_16x16x32_bf16 v[24:27], v[164:167], v[206:209], v[24:27]
	v_mfma_f32_16x16x32_bf16 v[16:19], v[148:151], v[214:217], v[16:19]
	v_mfma_f32_16x16x32_bf16 v[8:11], v[164:167], v[214:217], v[8:11]
	v_mfma_f32_16x16x32_bf16 v[52:55], v[168:171], v[186:189], v[52:55]
	v_mfma_f32_16x16x32_bf16 v[44:47], v[176:179], v[186:189], v[44:47]
	v_mfma_f32_16x16x32_bf16 v[36:39], v[168:171], v[194:197], v[36:39]
	v_mfma_f32_16x16x32_bf16 v[28:31], v[176:179], v[194:197], v[28:31]
	v_mfma_f32_16x16x32_bf16 v[20:23], v[168:171], v[202:205], v[20:23]
	v_mfma_f32_16x16x32_bf16 v[12:15], v[176:179], v[202:205], v[12:15]
	v_mfma_f32_16x16x32_bf16 v[4:7], v[168:171], v[210:213], v[4:7]
	v_mfma_f32_16x16x32_bf16 v[0:3], v[176:179], v[210:213], v[0:3]
	v_mfma_f32_16x16x32_bf16 v[52:55], v[172:175], v[190:193], v[52:55]
	v_mfma_f32_16x16x32_bf16 v[44:47], v[182:185], v[190:193], v[44:47]
	v_mfma_f32_16x16x32_bf16 v[36:39], v[172:175], v[198:201], v[36:39]
	s_add_i32 s53, s53, 2
	v_mfma_f32_16x16x32_bf16 v[28:31], v[182:185], v[198:201], v[28:31]
	s_add_u32 s51, s51, 0x100
	v_mfma_f32_16x16x32_bf16 v[20:23], v[172:175], v[206:209], v[20:23]
	s_addc_u32 s52, s52, 0
	v_mfma_f32_16x16x32_bf16 v[12:15], v[182:185], v[206:209], v[12:15]
	s_cmp_gt_u32 s53, 41
	v_mfma_f32_16x16x32_bf16 v[4:7], v[172:175], v[214:217], v[4:7]
	s_mov_b64 s[26:27], s[4:5]
	v_mfma_f32_16x16x32_bf16 v[0:3], v[182:185], v[214:217], v[0:3]
	s_setprio 0
	s_barrier
	s_cbranch_scc0 .LBB0_999
	s_and_b64 vcc, exec, s[12:13]
	s_cbranch_vccz .LBB0_1002
	s_barrier
